# plus: write-through (sc1) stores for the big streaming outputs of P1 (ZA/G) and P5 (A2): less L2 pollution, write-back spread over the phase
# baseline (speedup 1.0000x reference)
; __device__ __forceinline__ unsigned cvt_pk_bf16(float lo, float hi) { unsigned r; asm volatile("v_cvt_pk_bf16_f32 %0, %1, %2" : "=v"(r) : "v"(lo), "v"(hi)); return r; }
;     __device__ __forceinline__ void operator()(Acc& acc, const Unit& u, int slot, int cslot, int wr, int wc, int fr, int fq, LAS unsigned char* lds) const {
;     ...
; #pragma unroll
;         for (int ai = 0; ai < 2; ++ai)
; #pragma unroll
;             for (int m = 0; m < 4; ++m) {
;                 const int tr = TROW(ai, m); const size_t row = (size_t)u.pm * BM + tr; const float s = RS[tr]; float ss = 0.f;
;                 bf16_t* rowp = base + row * ld + colt + wc * 32 + 8 * fq;
; #pragma unroll
;                 for (int bj = 0; bj < 2; ++bj) { const f32x4 v0 = acc[ai][bj][m][0] * s, v1 = acc[ai][bj][m][1] * s;
;                     ss += (v0[0] * v0[0] + v0[1] * v0[1]) + (v0[2] * v0[2] + v0[3] * v0[3]) + (v1[0] * v1[0] + v1[1] * v1[1]) + (v1[2] * v1[2] + v1[3] * v1[3]);
;                     u32x4 w; w.x = cvt_pk_bf16(v0[0], v0[1]); w.y = cvt_pk_bf16(v0[2], v0[3]); w.z = cvt_pk_bf16(v1[0], v1[1]); w.w = cvt_pk_bf16(v1[2], v1[3]);
;                     *(u32x4*)(rowp + bj * HALF) = w; }
;                 if (sq) { ss += __shfl_xor(ss, 16); ss += __shfl_xor(ss, 32); if (fq == 0) sq[row * 8 + (pn & 1) * 4 + wc] = ss; }
.LBB0_276:
	s_cmp_lt_i32 s22, 4
	s_cselect_b64 s[54:55], -1, 0
	s_lshl_b32 s4, s22, 8
	s_add_i32 s5, s4, 0xfffffc00
	s_cmp_lt_i32 s22, 2
	v_readlane_b32 s6, v247, 21
	v_readlane_b32 s7, v247, 18
	v_readlane_b32 s15, v247, 22
	s_cselect_b32 s6, s6, s84
	s_cselect_b32 s7, s15, s7
	s_cmp_gt_i32 s22, 3
	s_cselect_b32 s4, s5, s4
	s_cselect_b32 s7, 0, s7
	s_cselect_b32 s6, 0, s6
	s_cselect_b32 s15, s39, s17
	s_cselect_b32 s43, s38, s16
	s_ashr_i32 s5, s4, 31
	s_lshl_b64 s[4:5], s[4:5], 1
	s_add_u32 s4, s43, s4
	s_addc_u32 s5, s15, s5
	s_lshl_b32 s15, s63, 1
	s_add_u32 s4, s4, s15
	s_addc_u32 s5, s5, 0
	s_lshl_b32 s15, s22, 4
	s_and_b32 s15, s15, 16
	s_add_u32 s6, s6, s15
	s_addc_u32 s7, s7, 0
	v_lshl_add_u64 v[140:141], v[138:139], 1, s[4:5]
	v_cmp_gt_u32_e64 s[4:5], 16, v134
	s_add_u32 s68, s6, s78
	ds_read_b32 v134, v170
	s_addc_u32 s69, s7, 0
	s_ashr_i32 s15, s14, 31
	s_lshl_b64 s[70:71], s[14:15], 8
	v_mov_b32_e32 v137, v135
	v_lshl_add_u64 v[142:143], s[70:71], 0, v[136:137]
	v_lshlrev_b64 v[144:145], 12, v[142:143]
	v_lshl_add_u64 v[176:177], v[140:141], 0, v[144:145]
	s_waitcnt lgkmcnt(0)
	v_pk_mul_f32 v[144:145], v[128:129], v[134:135] op_sel_hi:[1,0]
	v_pk_mul_f32 v[148:149], v[126:127], v[134:135] op_sel_hi:[1,0]
	v_pk_mul_f32 v[150:151], v[124:125], v[134:135] op_sel_hi:[1,0]
	v_pk_mul_f32 v[146:147], v[122:123], v[134:135] op_sel_hi:[1,0]
	v_cvt_pk_bf16_f32 v152, v148, v149
	v_cvt_pk_bf16_f32 v153, v144, v145
	v_pk_mul_f32 v[156:157], v[118:119], v[134:135] op_sel_hi:[1,0]
	v_cvt_pk_bf16_f32 v154, v146, v147
	v_cvt_pk_bf16_f32 v155, v150, v151
	global_store_dwordx4 v[176:177], v[152:155], off sc1
	v_pk_mul_f32 v[158:159], v[116:117], v[134:135] op_sel_hi:[1,0]
	s_and_b64 vcc, exec, s[54:55]
	v_pk_mul_f32 v[152:153], v[120:121], v[134:135] op_sel_hi:[1,0]
	v_pk_mul_f32 v[154:155], v[114:115], v[134:135] op_sel_hi:[1,0]
	v_cvt_pk_bf16_f32 v172, v156, v157
	v_cvt_pk_bf16_f32 v173, v152, v153
	s_nop 0
	v_cvt_pk_bf16_f32 v174, v154, v155
	v_cvt_pk_bf16_f32 v175, v158, v159
	global_store_dwordx4 v[176:177], v[172:175], off offset:256 sc1
	s_cbranch_vccz .LBB0_280
	v_mul_f32_e32 v137, v149, v149
	v_mul_f32_e32 v145, v145, v145
	v_fmac_f32_e32 v137, v148, v148
	v_fmac_f32_e32 v145, v144, v144
	v_mul_f32_e32 v144, v147, v147
	v_add_f32_e32 v137, v137, v145
	v_fmac_f32_e32 v144, v146, v146
	v_add_f32_e32 v137, v144, v137
	v_mul_f32_e32 v144, v157, v157
	v_mul_f32_e32 v145, v153, v153
	v_mul_f32_e32 v134, v151, v151
	v_fmac_f32_e32 v144, v156, v156
	v_fmac_f32_e32 v145, v152, v152
	v_fmac_f32_e32 v134, v150, v150
	v_add_f32_e32 v144, v144, v145
	v_mul_f32_e32 v145, v155, v155
	v_add_f32_e32 v134, v134, v137
	v_mul_f32_e32 v137, v159, v159
	v_fmac_f32_e32 v145, v154, v154
	v_fmac_f32_e32 v137, v158, v158
	v_add_f32_e32 v144, v145, v144
	v_add_f32_e32 v137, v137, v144
	v_and_b32_e32 v144, 64, v169
	v_add_f32_e32 v134, v134, v137
	v_xor_b32_e32 v137, 16, v169
	v_add_u32_e32 v144, 64, v144
	v_cmp_lt_i32_e32 vcc, v137, v144
	s_nop 1
	v_cndmask_b32_e32 v137, v169, v137, vcc
	v_lshlrev_b32_e32 v137, 2, v137
	ds_bpermute_b32 v137, v137, v134
	s_waitcnt lgkmcnt(0)
	v_add_f32_e32 v134, v134, v137
	v_xor_b32_e32 v137, 32, v169
	v_cmp_lt_i32_e32 vcc, v137, v144
	s_nop 1
	v_cndmask_b32_e32 v137, v169, v137, vcc
	v_lshlrev_b32_e32 v137, 2, v137
	ds_bpermute_b32 v137, v137, v134
	s_and_saveexec_b64 s[6:7], s[4:5]
	s_cbranch_execz .LBB0_279
	v_lshlrev_b64 v[142:143], 5, v[142:143]
	v_lshl_add_u64 v[142:143], s[68:69], 0, v[142:143]
	s_waitcnt lgkmcnt(0)
	v_add_f32_e32 v134, v134, v137
	global_store_dword v[142:143], v134, off

; __device__ __forceinline__ unsigned cvt_pk_bf16(float lo, float hi) { unsigned r; asm volatile("v_cvt_pk_bf16_f32 %0, %1, %2" : "=v"(r) : "v"(lo), "v"(hi)); return r; }
;     __device__ __forceinline__ void operator()(Acc& acc, const Unit& u, int slot, int cslot, int wr, int wc, int fr, int fq, LAS unsigned char* lds) const {
;     ...
; #pragma unroll
;         for (int ai = 0; ai < 2; ++ai)
; #pragma unroll
;             for (int m = 0; m < 4; ++m) {
;                 const int tr = TROW(ai, m); const size_t row = (size_t)u.pm * BM + tr; const float s = RS[tr]; float ss = 0.f;
;                 bf16_t* rowp = base + row * ld + colt + wc * 32 + 8 * fq;
; #pragma unroll
;                 for (int bj = 0; bj < 2; ++bj) { const f32x4 v0 = acc[ai][bj][m][0] * s, v1 = acc[ai][bj][m][1] * s;
;                     ss += (v0[0] * v0[0] + v0[1] * v0[1]) + (v0[2] * v0[2] + v0[3] * v0[3]) + (v1[0] * v1[0] + v1[1] * v1[1]) + (v1[2] * v1[2] + v1[3] * v1[3]);
;                     u32x4 w; w.x = cvt_pk_bf16(v0[0], v0[1]); w.y = cvt_pk_bf16(v0[2], v0[3]); w.z = cvt_pk_bf16(v1[0], v1[1]); w.w = cvt_pk_bf16(v1[2], v1[3]);
;                     *(u32x4*)(rowp + bj * HALF) = w; }
;                 if (sq) { ss += __shfl_xor(ss, 16); ss += __shfl_xor(ss, 32); if (fq == 0) sq[row * 8 + (pn & 1) * 4 + wc] = ss; }
.LBB0_280:
	ds_read_b32 v172, v170 offset:64
	v_or_b32_e32 v134, 16, v136
	v_lshl_add_u64 v[142:143], s[70:71], 0, v[134:135]
	v_lshlrev_b64 v[144:145], 12, v[142:143]
	v_lshl_add_u64 v[176:177], v[140:141], 0, v[144:145]
	s_waitcnt lgkmcnt(0)
	v_pk_mul_f32 v[144:145], v[112:113], v[172:173] op_sel_hi:[1,0]
	v_pk_mul_f32 v[148:149], v[110:111], v[172:173] op_sel_hi:[1,0]
	v_pk_mul_f32 v[150:151], v[108:109], v[172:173] op_sel_hi:[1,0]
	v_pk_mul_f32 v[146:147], v[106:107], v[172:173] op_sel_hi:[1,0]
	v_cvt_pk_bf16_f32 v152, v148, v149
	v_cvt_pk_bf16_f32 v153, v144, v145
	v_cndmask_b32_e64 v134, 0, 1, s[54:55]
	v_cvt_pk_bf16_f32 v154, v146, v147
	v_cvt_pk_bf16_f32 v155, v150, v151
	global_store_dwordx4 v[176:177], v[152:155], off sc1
	v_pk_mul_f32 v[156:157], v[102:103], v[172:173] op_sel_hi:[1,0]
	v_pk_mul_f32 v[158:159], v[100:101], v[172:173] op_sel_hi:[1,0]
	v_pk_mul_f32 v[152:153], v[104:105], v[172:173] op_sel_hi:[1,0]
	v_pk_mul_f32 v[154:155], v[98:99], v[172:173] op_sel_hi:[1,0]
	v_cmp_ne_u32_e64 s[6:7], 1, v134
	s_andn2_b64 vcc, exec, s[54:55]
	v_cvt_pk_bf16_f32 v172, v156, v157
	v_cvt_pk_bf16_f32 v173, v152, v153
	v_cvt_pk_bf16_f32 v174, v154, v155
	v_cvt_pk_bf16_f32 v175, v158, v159
	global_store_dwordx4 v[176:177], v[172:175], off offset:256 sc1
	s_cbranch_vccnz .LBB0_284
	v_mul_f32_e32 v137, v149, v149
	v_mul_f32_e32 v145, v145, v145
	v_fmac_f32_e32 v137, v148, v148
	v_fmac_f32_e32 v145, v144, v144
	v_mul_f32_e32 v144, v147, v147
	v_add_f32_e32 v137, v137, v145
	v_fmac_f32_e32 v144, v146, v146
	v_add_f32_e32 v137, v144, v137
	v_mul_f32_e32 v144, v157, v157
	v_mul_f32_e32 v145, v153, v153
	v_mul_f32_e32 v134, v151, v151
	v_fmac_f32_e32 v144, v156, v156
	v_fmac_f32_e32 v145, v152, v152
	v_fmac_f32_e32 v134, v150, v150
	v_add_f32_e32 v144, v144, v145
	v_mul_f32_e32 v145, v155, v155
	v_add_f32_e32 v134, v134, v137
	v_mul_f32_e32 v137, v159, v159
	v_fmac_f32_e32 v145, v154, v154
	v_fmac_f32_e32 v137, v158, v158
	v_add_f32_e32 v144, v145, v144
	v_add_f32_e32 v137, v137, v144
	v_and_b32_e32 v144, 64, v169
	v_add_f32_e32 v134, v134, v137
	v_xor_b32_e32 v137, 16, v169
	v_add_u32_e32 v144, 64, v144
	v_cmp_lt_i32_e32 vcc, v137, v144
	s_nop 1
	v_cndmask_b32_e32 v137, v169, v137, vcc
	v_lshlrev_b32_e32 v137, 2, v137
	ds_bpermute_b32 v137, v137, v134
	s_waitcnt lgkmcnt(0)
	v_add_f32_e32 v134, v134, v137
	v_xor_b32_e32 v137, 32, v169
	v_cmp_lt_i32_e32 vcc, v137, v144
	s_nop 1
	v_cndmask_b32_e32 v137, v169, v137, vcc
	v_lshlrev_b32_e32 v137, 2, v137
	ds_bpermute_b32 v137, v137, v134
	s_and_saveexec_b64 s[54:55], s[4:5]
	s_cbranch_execz .LBB0_283
	v_lshlrev_b64 v[142:143], 5, v[142:143]
	v_lshl_add_u64 v[142:143], s[68:69], 0, v[142:143]
	s_waitcnt lgkmcnt(0)
	v_add_f32_e32 v134, v134, v137
	global_store_dword v[142:143], v134, off

; __device__ __forceinline__ unsigned cvt_pk_bf16(float lo, float hi) { unsigned r; asm volatile("v_cvt_pk_bf16_f32 %0, %1, %2" : "=v"(r) : "v"(lo), "v"(hi)); return r; }
;     __device__ __forceinline__ void operator()(Acc& acc, const Unit& u, int slot, int cslot, int wr, int wc, int fr, int fq, LAS unsigned char* lds) const {
;     ...
; #pragma unroll
;         for (int ai = 0; ai < 2; ++ai)
; #pragma unroll
;             for (int m = 0; m < 4; ++m) {
;                 const int tr = TROW(ai, m); const size_t row = (size_t)u.pm * BM + tr; const float s = RS[tr]; float ss = 0.f;
;                 bf16_t* rowp = base + row * ld + colt + wc * 32 + 8 * fq;
; #pragma unroll
;                 for (int bj = 0; bj < 2; ++bj) { const f32x4 v0 = acc[ai][bj][m][0] * s, v1 = acc[ai][bj][m][1] * s;
;                     ss += (v0[0] * v0[0] + v0[1] * v0[1]) + (v0[2] * v0[2] + v0[3] * v0[3]) + (v1[0] * v1[0] + v1[1] * v1[1]) + (v1[2] * v1[2] + v1[3] * v1[3]);
;                     u32x4 w; w.x = cvt_pk_bf16(v0[0], v0[1]); w.y = cvt_pk_bf16(v0[2], v0[3]); w.z = cvt_pk_bf16(v1[0], v1[1]); w.w = cvt_pk_bf16(v1[2], v1[3]);
;                     *(u32x4*)(rowp + bj * HALF) = w; }
;                 if (sq) { ss += __shfl_xor(ss, 16); ss += __shfl_xor(ss, 32); if (fq == 0) sq[row * 8 + (pn & 1) * 4 + wc] = ss; }
.LBB0_284:
	ds_read_b32 v172, v170 offset:128
	v_or_b32_e32 v134, 32, v136
	v_lshl_add_u64 v[142:143], s[70:71], 0, v[134:135]
	v_lshlrev_b64 v[144:145], 12, v[142:143]
	v_lshl_add_u64 v[176:177], v[140:141], 0, v[144:145]
	s_waitcnt lgkmcnt(0)
	v_pk_mul_f32 v[144:145], v[96:97], v[172:173] op_sel_hi:[1,0]
	v_pk_mul_f32 v[148:149], v[94:95], v[172:173] op_sel_hi:[1,0]
	v_pk_mul_f32 v[150:151], v[92:93], v[172:173] op_sel_hi:[1,0]
	v_pk_mul_f32 v[146:147], v[90:91], v[172:173] op_sel_hi:[1,0]
	v_cvt_pk_bf16_f32 v152, v148, v149
	v_cvt_pk_bf16_f32 v153, v144, v145
	v_pk_mul_f32 v[156:157], v[86:87], v[172:173] op_sel_hi:[1,0]
	v_cvt_pk_bf16_f32 v154, v146, v147
	v_cvt_pk_bf16_f32 v155, v150, v151
	global_store_dwordx4 v[176:177], v[152:155], off sc1
	v_pk_mul_f32 v[158:159], v[84:85], v[172:173] op_sel_hi:[1,0]
	s_and_b64 vcc, exec, s[6:7]
	v_pk_mul_f32 v[152:153], v[88:89], v[172:173] op_sel_hi:[1,0]
	v_pk_mul_f32 v[154:155], v[82:83], v[172:173] op_sel_hi:[1,0]
	v_cvt_pk_bf16_f32 v172, v156, v157
	v_cvt_pk_bf16_f32 v173, v152, v153
	s_nop 0
	v_cvt_pk_bf16_f32 v174, v154, v155
	v_cvt_pk_bf16_f32 v175, v158, v159
	global_store_dwordx4 v[176:177], v[172:175], off offset:256 sc1
	s_cbranch_vccnz .LBB0_288
	v_mul_f32_e32 v137, v149, v149
	v_mul_f32_e32 v145, v145, v145
	v_fmac_f32_e32 v137, v148, v148
	v_fmac_f32_e32 v145, v144, v144
	v_mul_f32_e32 v144, v147, v147
	v_add_f32_e32 v137, v137, v145
	v_fmac_f32_e32 v144, v146, v146
	v_add_f32_e32 v137, v144, v137
	v_mul_f32_e32 v144, v157, v157
	v_mul_f32_e32 v145, v153, v153
	v_mul_f32_e32 v134, v151, v151
	v_fmac_f32_e32 v144, v156, v156
	v_fmac_f32_e32 v145, v152, v152
	v_fmac_f32_e32 v134, v150, v150
	v_add_f32_e32 v144, v144, v145
	v_mul_f32_e32 v145, v155, v155
	v_add_f32_e32 v134, v134, v137
	v_mul_f32_e32 v137, v159, v159
	v_fmac_f32_e32 v145, v154, v154
	v_fmac_f32_e32 v137, v158, v158
	v_add_f32_e32 v144, v145, v144
	v_add_f32_e32 v137, v137, v144
	v_and_b32_e32 v144, 64, v169
	v_add_f32_e32 v134, v134, v137
	v_xor_b32_e32 v137, 16, v169
	v_add_u32_e32 v144, 64, v144
	v_cmp_lt_i32_e32 vcc, v137, v144
	s_nop 1
	v_cndmask_b32_e32 v137, v169, v137, vcc
	v_lshlrev_b32_e32 v137, 2, v137
	ds_bpermute_b32 v137, v137, v134
	s_waitcnt lgkmcnt(0)
	v_add_f32_e32 v134, v134, v137
	v_xor_b32_e32 v137, 32, v169
	v_cmp_lt_i32_e32 vcc, v137, v144
	s_nop 1
	v_cndmask_b32_e32 v137, v169, v137, vcc
	v_lshlrev_b32_e32 v137, 2, v137
	ds_bpermute_b32 v137, v137, v134
	s_and_saveexec_b64 s[54:55], s[4:5]
	s_cbranch_execz .LBB0_287
	v_lshlrev_b64 v[142:143], 5, v[142:143]
	v_lshl_add_u64 v[142:143], s[68:69], 0, v[142:143]
	s_waitcnt lgkmcnt(0)
	v_add_f32_e32 v134, v134, v137
	global_store_dword v[142:143], v134, off

; __device__ __forceinline__ unsigned cvt_pk_bf16(float lo, float hi) { unsigned r; asm volatile("v_cvt_pk_bf16_f32 %0, %1, %2" : "=v"(r) : "v"(lo), "v"(hi)); return r; }
;     __device__ __forceinline__ void operator()(Acc& acc, const Unit& u, int slot, int cslot, int wr, int wc, int fr, int fq, LAS unsigned char* lds) const {
;     ...
; #pragma unroll
;         for (int ai = 0; ai < 2; ++ai)
; #pragma unroll
;             for (int m = 0; m < 4; ++m) {
;                 const int tr = TROW(ai, m); const size_t row = (size_t)u.pm * BM + tr; const float s = RS[tr]; float ss = 0.f;
;                 bf16_t* rowp = base + row * ld + colt + wc * 32 + 8 * fq;
; #pragma unroll
;                 for (int bj = 0; bj < 2; ++bj) { const f32x4 v0 = acc[ai][bj][m][0] * s, v1 = acc[ai][bj][m][1] * s;
;                     ss += (v0[0] * v0[0] + v0[1] * v0[1]) + (v0[2] * v0[2] + v0[3] * v0[3]) + (v1[0] * v1[0] + v1[1] * v1[1]) + (v1[2] * v1[2] + v1[3] * v1[3]);
;                     u32x4 w; w.x = cvt_pk_bf16(v0[0], v0[1]); w.y = cvt_pk_bf16(v0[2], v0[3]); w.z = cvt_pk_bf16(v1[0], v1[1]); w.w = cvt_pk_bf16(v1[2], v1[3]);
;                     *(u32x4*)(rowp + bj * HALF) = w; }
;                 if (sq) { ss += __shfl_xor(ss, 16); ss += __shfl_xor(ss, 32); if (fq == 0) sq[row * 8 + (pn & 1) * 4 + wc] = ss; }
.LBB0_288:
	ds_read_b32 v172, v170 offset:192
	v_or_b32_e32 v134, 48, v136
	v_lshl_add_u64 v[142:143], s[70:71], 0, v[134:135]
	v_lshlrev_b64 v[144:145], 12, v[142:143]
	v_lshl_add_u64 v[176:177], v[140:141], 0, v[144:145]
	s_waitcnt lgkmcnt(0)
	v_pk_mul_f32 v[144:145], v[80:81], v[172:173] op_sel_hi:[1,0]
	v_pk_mul_f32 v[148:149], v[78:79], v[172:173] op_sel_hi:[1,0]
	v_pk_mul_f32 v[150:151], v[76:77], v[172:173] op_sel_hi:[1,0]
	v_pk_mul_f32 v[146:147], v[74:75], v[172:173] op_sel_hi:[1,0]
	v_cvt_pk_bf16_f32 v152, v148, v149
	v_cvt_pk_bf16_f32 v153, v144, v145
	v_pk_mul_f32 v[156:157], v[70:71], v[172:173] op_sel_hi:[1,0]
	v_cvt_pk_bf16_f32 v154, v146, v147
	v_cvt_pk_bf16_f32 v155, v150, v151
	global_store_dwordx4 v[176:177], v[152:155], off sc1
	v_pk_mul_f32 v[158:159], v[68:69], v[172:173] op_sel_hi:[1,0]
	s_and_b64 vcc, exec, s[6:7]
	v_pk_mul_f32 v[152:153], v[72:73], v[172:173] op_sel_hi:[1,0]
	v_pk_mul_f32 v[154:155], v[66:67], v[172:173] op_sel_hi:[1,0]
	v_cvt_pk_bf16_f32 v172, v156, v157
	v_cvt_pk_bf16_f32 v173, v152, v153
	s_nop 0
	v_cvt_pk_bf16_f32 v174, v154, v155
	v_cvt_pk_bf16_f32 v175, v158, v159
	global_store_dwordx4 v[176:177], v[172:175], off offset:256 sc1
	s_cbranch_vccnz .LBB0_292
	v_mul_f32_e32 v137, v149, v149
	v_mul_f32_e32 v145, v145, v145
	v_fmac_f32_e32 v137, v148, v148
	v_fmac_f32_e32 v145, v144, v144
	v_mul_f32_e32 v144, v147, v147
	v_add_f32_e32 v137, v137, v145
	v_fmac_f32_e32 v144, v146, v146
	v_add_f32_e32 v137, v144, v137
	v_mul_f32_e32 v144, v157, v157
	v_mul_f32_e32 v145, v153, v153
	v_mul_f32_e32 v134, v151, v151
	v_fmac_f32_e32 v144, v156, v156
	v_fmac_f32_e32 v145, v152, v152
	v_fmac_f32_e32 v134, v150, v150
	v_add_f32_e32 v144, v144, v145
	v_mul_f32_e32 v145, v155, v155
	v_add_f32_e32 v134, v134, v137
	v_mul_f32_e32 v137, v159, v159
	v_fmac_f32_e32 v145, v154, v154
	v_fmac_f32_e32 v137, v158, v158
	v_add_f32_e32 v144, v145, v144
	v_add_f32_e32 v137, v137, v144
	v_and_b32_e32 v144, 64, v169
	v_add_f32_e32 v134, v134, v137
	v_xor_b32_e32 v137, 16, v169
	v_add_u32_e32 v144, 64, v144
	v_cmp_lt_i32_e32 vcc, v137, v144
	s_nop 1
	v_cndmask_b32_e32 v137, v169, v137, vcc
	v_lshlrev_b32_e32 v137, 2, v137
	ds_bpermute_b32 v137, v137, v134
	s_waitcnt lgkmcnt(0)
	v_add_f32_e32 v134, v134, v137
	v_xor_b32_e32 v137, 32, v169
	v_cmp_lt_i32_e32 vcc, v137, v144
	s_nop 1
	v_cndmask_b32_e32 v137, v169, v137, vcc
	v_lshlrev_b32_e32 v137, 2, v137
	ds_bpermute_b32 v137, v137, v134
	s_and_saveexec_b64 s[54:55], s[4:5]
	s_cbranch_execz .LBB0_291
	v_lshlrev_b64 v[142:143], 5, v[142:143]
	v_lshl_add_u64 v[142:143], s[68:69], 0, v[142:143]
	s_waitcnt lgkmcnt(0)
	v_add_f32_e32 v134, v134, v137
	global_store_dword v[142:143], v134, off

; __device__ __forceinline__ unsigned cvt_pk_bf16(float lo, float hi) { unsigned r; asm volatile("v_cvt_pk_bf16_f32 %0, %1, %2" : "=v"(r) : "v"(lo), "v"(hi)); return r; }
;     __device__ __forceinline__ void operator()(Acc& acc, const Unit& u, int slot, int cslot, int wr, int wc, int fr, int fq, LAS unsigned char* lds) const {
;     ...
; #pragma unroll
;         for (int ai = 0; ai < 2; ++ai)
; #pragma unroll
;             for (int m = 0; m < 4; ++m) {
;                 const int tr = TROW(ai, m); const size_t row = (size_t)u.pm * BM + tr; const float s = RS[tr]; float ss = 0.f;
;                 bf16_t* rowp = base + row * ld + colt + wc * 32 + 8 * fq;
; #pragma unroll
;                 for (int bj = 0; bj < 2; ++bj) { const f32x4 v0 = acc[ai][bj][m][0] * s, v1 = acc[ai][bj][m][1] * s;
;                     ss += (v0[0] * v0[0] + v0[1] * v0[1]) + (v0[2] * v0[2] + v0[3] * v0[3]) + (v1[0] * v1[0] + v1[1] * v1[1]) + (v1[2] * v1[2] + v1[3] * v1[3]);
;                     u32x4 w; w.x = cvt_pk_bf16(v0[0], v0[1]); w.y = cvt_pk_bf16(v0[2], v0[3]); w.z = cvt_pk_bf16(v1[0], v1[1]); w.w = cvt_pk_bf16(v1[2], v1[3]);
;                     *(u32x4*)(rowp + bj * HALF) = w; }
;                 if (sq) { ss += __shfl_xor(ss, 16); ss += __shfl_xor(ss, 32); if (fq == 0) sq[row * 8 + (pn & 1) * 4 + wc] = ss; }
.LBB0_292:
	ds_read_b32 v172, v170 offset:512
	v_add_u32_e32 v134, 0x80, v136
	v_lshl_add_u64 v[142:143], s[70:71], 0, v[134:135]
	v_lshlrev_b64 v[144:145], 12, v[142:143]
	v_lshl_add_u64 v[176:177], v[140:141], 0, v[144:145]
	s_waitcnt lgkmcnt(0)
	v_pk_mul_f32 v[144:145], v[64:65], v[172:173] op_sel_hi:[1,0]
	v_pk_mul_f32 v[148:149], v[62:63], v[172:173] op_sel_hi:[1,0]
	v_pk_mul_f32 v[150:151], v[60:61], v[172:173] op_sel_hi:[1,0]
	v_pk_mul_f32 v[146:147], v[58:59], v[172:173] op_sel_hi:[1,0]
	v_cvt_pk_bf16_f32 v152, v148, v149
	v_cvt_pk_bf16_f32 v153, v144, v145
	v_pk_mul_f32 v[156:157], v[54:55], v[172:173] op_sel_hi:[1,0]
	v_cvt_pk_bf16_f32 v154, v146, v147
	v_cvt_pk_bf16_f32 v155, v150, v151
	global_store_dwordx4 v[176:177], v[152:155], off sc1
	v_pk_mul_f32 v[158:159], v[52:53], v[172:173] op_sel_hi:[1,0]
	s_and_b64 vcc, exec, s[6:7]
	v_pk_mul_f32 v[152:153], v[56:57], v[172:173] op_sel_hi:[1,0]
	v_pk_mul_f32 v[154:155], v[50:51], v[172:173] op_sel_hi:[1,0]
	v_cvt_pk_bf16_f32 v172, v156, v157
	v_cvt_pk_bf16_f32 v173, v152, v153
	s_nop 0
	v_cvt_pk_bf16_f32 v174, v154, v155
	v_cvt_pk_bf16_f32 v175, v158, v159
	global_store_dwordx4 v[176:177], v[172:175], off offset:256 sc1
	s_cbranch_vccnz .LBB0_296
	v_mul_f32_e32 v137, v149, v149
	v_mul_f32_e32 v145, v145, v145
	v_fmac_f32_e32 v137, v148, v148
	v_fmac_f32_e32 v145, v144, v144
	v_mul_f32_e32 v144, v147, v147
	v_add_f32_e32 v137, v137, v145
	v_fmac_f32_e32 v144, v146, v146
	v_add_f32_e32 v137, v144, v137
	v_mul_f32_e32 v144, v157, v157
	v_mul_f32_e32 v145, v153, v153
	v_mul_f32_e32 v134, v151, v151
	v_fmac_f32_e32 v144, v156, v156
	v_fmac_f32_e32 v145, v152, v152
	v_fmac_f32_e32 v134, v150, v150
	v_add_f32_e32 v144, v144, v145
	v_mul_f32_e32 v145, v155, v155
	v_add_f32_e32 v134, v134, v137
	v_mul_f32_e32 v137, v159, v159
	v_fmac_f32_e32 v145, v154, v154
	v_fmac_f32_e32 v137, v158, v158
	v_add_f32_e32 v144, v145, v144
	v_add_f32_e32 v137, v137, v144
	v_and_b32_e32 v144, 64, v169
	v_add_f32_e32 v134, v134, v137
	v_xor_b32_e32 v137, 16, v169
	v_add_u32_e32 v144, 64, v144
	v_cmp_lt_i32_e32 vcc, v137, v144
	s_nop 1
	v_cndmask_b32_e32 v137, v169, v137, vcc
	v_lshlrev_b32_e32 v137, 2, v137
	ds_bpermute_b32 v137, v137, v134
	s_waitcnt lgkmcnt(0)
	v_add_f32_e32 v134, v134, v137
	v_xor_b32_e32 v137, 32, v169
	v_cmp_lt_i32_e32 vcc, v137, v144
	s_nop 1
	v_cndmask_b32_e32 v137, v169, v137, vcc
	v_lshlrev_b32_e32 v137, 2, v137
	ds_bpermute_b32 v137, v137, v134
	s_and_saveexec_b64 s[54:55], s[4:5]
	s_cbranch_execz .LBB0_295
	v_lshlrev_b64 v[142:143], 5, v[142:143]
	v_lshl_add_u64 v[142:143], s[68:69], 0, v[142:143]
	s_waitcnt lgkmcnt(0)
	v_add_f32_e32 v134, v134, v137
	global_store_dword v[142:143], v134, off

; __device__ __forceinline__ unsigned cvt_pk_bf16(float lo, float hi) { unsigned r; asm volatile("v_cvt_pk_bf16_f32 %0, %1, %2" : "=v"(r) : "v"(lo), "v"(hi)); return r; }
;     __device__ __forceinline__ void operator()(Acc& acc, const Unit& u, int slot, int cslot, int wr, int wc, int fr, int fq, LAS unsigned char* lds) const {
;     ...
; #pragma unroll
;         for (int ai = 0; ai < 2; ++ai)
; #pragma unroll
;             for (int m = 0; m < 4; ++m) {
;                 const int tr = TROW(ai, m); const size_t row = (size_t)u.pm * BM + tr; const float s = RS[tr]; float ss = 0.f;
;                 bf16_t* rowp = base + row * ld + colt + wc * 32 + 8 * fq;
; #pragma unroll
;                 for (int bj = 0; bj < 2; ++bj) { const f32x4 v0 = acc[ai][bj][m][0] * s, v1 = acc[ai][bj][m][1] * s;
;                     ss += (v0[0] * v0[0] + v0[1] * v0[1]) + (v0[2] * v0[2] + v0[3] * v0[3]) + (v1[0] * v1[0] + v1[1] * v1[1]) + (v1[2] * v1[2] + v1[3] * v1[3]);
;                     u32x4 w; w.x = cvt_pk_bf16(v0[0], v0[1]); w.y = cvt_pk_bf16(v0[2], v0[3]); w.z = cvt_pk_bf16(v1[0], v1[1]); w.w = cvt_pk_bf16(v1[2], v1[3]);
;                     *(u32x4*)(rowp + bj * HALF) = w; }
;                 if (sq) { ss += __shfl_xor(ss, 16); ss += __shfl_xor(ss, 32); if (fq == 0) sq[row * 8 + (pn & 1) * 4 + wc] = ss; }
.LBB0_296:
	ds_read_b32 v172, v170 offset:576
	v_add_u32_e32 v134, 0x90, v136
	v_lshl_add_u64 v[142:143], s[70:71], 0, v[134:135]
	v_lshlrev_b64 v[144:145], 12, v[142:143]
	v_lshl_add_u64 v[176:177], v[140:141], 0, v[144:145]
	s_waitcnt lgkmcnt(0)
	v_pk_mul_f32 v[144:145], v[48:49], v[172:173] op_sel_hi:[1,0]
	v_pk_mul_f32 v[148:149], v[46:47], v[172:173] op_sel_hi:[1,0]
	v_pk_mul_f32 v[150:151], v[44:45], v[172:173] op_sel_hi:[1,0]
	v_pk_mul_f32 v[146:147], v[42:43], v[172:173] op_sel_hi:[1,0]
	v_cvt_pk_bf16_f32 v152, v148, v149
	v_cvt_pk_bf16_f32 v153, v144, v145
	v_pk_mul_f32 v[156:157], v[38:39], v[172:173] op_sel_hi:[1,0]
	v_cvt_pk_bf16_f32 v154, v146, v147
	v_cvt_pk_bf16_f32 v155, v150, v151
	global_store_dwordx4 v[176:177], v[152:155], off sc1
	v_pk_mul_f32 v[158:159], v[36:37], v[172:173] op_sel_hi:[1,0]
	s_and_b64 vcc, exec, s[6:7]
	v_pk_mul_f32 v[152:153], v[40:41], v[172:173] op_sel_hi:[1,0]
	v_pk_mul_f32 v[154:155], v[34:35], v[172:173] op_sel_hi:[1,0]
	v_cvt_pk_bf16_f32 v172, v156, v157
	v_cvt_pk_bf16_f32 v173, v152, v153
	s_nop 0
	v_cvt_pk_bf16_f32 v174, v154, v155
	v_cvt_pk_bf16_f32 v175, v158, v159
	global_store_dwordx4 v[176:177], v[172:175], off offset:256 sc1
	s_cbranch_vccnz .LBB0_300
	v_mul_f32_e32 v137, v149, v149
	v_mul_f32_e32 v145, v145, v145
	v_fmac_f32_e32 v137, v148, v148
	v_fmac_f32_e32 v145, v144, v144
	v_mul_f32_e32 v144, v147, v147
	v_add_f32_e32 v137, v137, v145
	v_fmac_f32_e32 v144, v146, v146
	v_add_f32_e32 v137, v144, v137
	v_mul_f32_e32 v144, v157, v157
	v_mul_f32_e32 v145, v153, v153
	v_mul_f32_e32 v134, v151, v151
	v_fmac_f32_e32 v144, v156, v156
	v_fmac_f32_e32 v145, v152, v152
	v_fmac_f32_e32 v134, v150, v150
	v_add_f32_e32 v144, v144, v145
	v_mul_f32_e32 v145, v155, v155
	v_add_f32_e32 v134, v134, v137
	v_mul_f32_e32 v137, v159, v159
	v_fmac_f32_e32 v145, v154, v154
	v_fmac_f32_e32 v137, v158, v158
	v_add_f32_e32 v144, v145, v144
	v_add_f32_e32 v137, v137, v144
	v_and_b32_e32 v144, 64, v169
	v_add_f32_e32 v134, v134, v137
	v_xor_b32_e32 v137, 16, v169
	v_add_u32_e32 v144, 64, v144
	v_cmp_lt_i32_e32 vcc, v137, v144
	s_nop 1
	v_cndmask_b32_e32 v137, v169, v137, vcc
	v_lshlrev_b32_e32 v137, 2, v137
	ds_bpermute_b32 v137, v137, v134
	s_waitcnt lgkmcnt(0)
	v_add_f32_e32 v134, v134, v137
	v_xor_b32_e32 v137, 32, v169
	v_cmp_lt_i32_e32 vcc, v137, v144
	s_nop 1
	v_cndmask_b32_e32 v137, v169, v137, vcc
	v_lshlrev_b32_e32 v137, 2, v137
	ds_bpermute_b32 v137, v137, v134
	s_and_saveexec_b64 s[54:55], s[4:5]
	s_cbranch_execz .LBB0_299
	v_lshlrev_b64 v[142:143], 5, v[142:143]
	v_lshl_add_u64 v[142:143], s[68:69], 0, v[142:143]
	s_waitcnt lgkmcnt(0)
	v_add_f32_e32 v134, v134, v137
	global_store_dword v[142:143], v134, off

; __device__ __forceinline__ unsigned cvt_pk_bf16(float lo, float hi) { unsigned r; asm volatile("v_cvt_pk_bf16_f32 %0, %1, %2" : "=v"(r) : "v"(lo), "v"(hi)); return r; }
;     __device__ __forceinline__ void operator()(Acc& acc, const Unit& u, int slot, int cslot, int wr, int wc, int fr, int fq, LAS unsigned char* lds) const {
;     ...
; #pragma unroll
;         for (int ai = 0; ai < 2; ++ai)
; #pragma unroll
;             for (int m = 0; m < 4; ++m) {
;                 const int tr = TROW(ai, m); const size_t row = (size_t)u.pm * BM + tr; const float s = RS[tr]; float ss = 0.f;
;                 bf16_t* rowp = base + row * ld + colt + wc * 32 + 8 * fq;
; #pragma unroll
;                 for (int bj = 0; bj < 2; ++bj) { const f32x4 v0 = acc[ai][bj][m][0] * s, v1 = acc[ai][bj][m][1] * s;
;                     ss += (v0[0] * v0[0] + v0[1] * v0[1]) + (v0[2] * v0[2] + v0[3] * v0[3]) + (v1[0] * v1[0] + v1[1] * v1[1]) + (v1[2] * v1[2] + v1[3] * v1[3]);
;                     u32x4 w; w.x = cvt_pk_bf16(v0[0], v0[1]); w.y = cvt_pk_bf16(v0[2], v0[3]); w.z = cvt_pk_bf16(v1[0], v1[1]); w.w = cvt_pk_bf16(v1[2], v1[3]);
;                     *(u32x4*)(rowp + bj * HALF) = w; }
;                 if (sq) { ss += __shfl_xor(ss, 16); ss += __shfl_xor(ss, 32); if (fq == 0) sq[row * 8 + (pn & 1) * 4 + wc] = ss; }
.LBB0_300:
	ds_read_b32 v172, v170 offset:640
	v_add_u32_e32 v134, 0xa0, v136
	v_lshl_add_u64 v[142:143], s[70:71], 0, v[134:135]
	v_lshlrev_b64 v[144:145], 12, v[142:143]
	v_lshl_add_u64 v[176:177], v[140:141], 0, v[144:145]
	s_waitcnt lgkmcnt(0)
	v_pk_mul_f32 v[144:145], v[32:33], v[172:173] op_sel_hi:[1,0]
	v_pk_mul_f32 v[148:149], v[30:31], v[172:173] op_sel_hi:[1,0]
	v_pk_mul_f32 v[150:151], v[28:29], v[172:173] op_sel_hi:[1,0]
	v_pk_mul_f32 v[146:147], v[26:27], v[172:173] op_sel_hi:[1,0]
	v_cvt_pk_bf16_f32 v152, v148, v149
	v_cvt_pk_bf16_f32 v153, v144, v145
	v_pk_mul_f32 v[156:157], v[22:23], v[172:173] op_sel_hi:[1,0]
	v_cvt_pk_bf16_f32 v154, v146, v147
	v_cvt_pk_bf16_f32 v155, v150, v151
	global_store_dwordx4 v[176:177], v[152:155], off sc1
	v_pk_mul_f32 v[158:159], v[20:21], v[172:173] op_sel_hi:[1,0]
	s_and_b64 vcc, exec, s[6:7]
	v_pk_mul_f32 v[152:153], v[24:25], v[172:173] op_sel_hi:[1,0]
	v_pk_mul_f32 v[154:155], v[18:19], v[172:173] op_sel_hi:[1,0]
	v_cvt_pk_bf16_f32 v172, v156, v157
	v_cvt_pk_bf16_f32 v173, v152, v153
	s_nop 0
	v_cvt_pk_bf16_f32 v174, v154, v155
	v_cvt_pk_bf16_f32 v175, v158, v159
	global_store_dwordx4 v[176:177], v[172:175], off offset:256 sc1
	s_cbranch_vccnz .LBB0_304
	v_mul_f32_e32 v137, v149, v149
	v_mul_f32_e32 v145, v145, v145
	v_fmac_f32_e32 v137, v148, v148
	v_fmac_f32_e32 v145, v144, v144
	v_mul_f32_e32 v144, v147, v147
	v_add_f32_e32 v137, v137, v145
	v_fmac_f32_e32 v144, v146, v146
	v_add_f32_e32 v137, v144, v137
	v_mul_f32_e32 v144, v157, v157
	v_mul_f32_e32 v145, v153, v153
	v_mul_f32_e32 v134, v151, v151
	v_fmac_f32_e32 v144, v156, v156
	v_fmac_f32_e32 v145, v152, v152
	v_fmac_f32_e32 v134, v150, v150
	v_add_f32_e32 v144, v144, v145
	v_mul_f32_e32 v145, v155, v155
	v_add_f32_e32 v134, v134, v137
	v_mul_f32_e32 v137, v159, v159
	v_fmac_f32_e32 v145, v154, v154
	v_fmac_f32_e32 v137, v158, v158
	v_add_f32_e32 v144, v145, v144
	v_add_f32_e32 v137, v137, v144
	v_and_b32_e32 v144, 64, v169
	v_add_f32_e32 v134, v134, v137
	v_xor_b32_e32 v137, 16, v169
	v_add_u32_e32 v144, 64, v144
	v_cmp_lt_i32_e32 vcc, v137, v144
	s_nop 1
	v_cndmask_b32_e32 v137, v169, v137, vcc
	v_lshlrev_b32_e32 v137, 2, v137
	ds_bpermute_b32 v137, v137, v134
	s_waitcnt lgkmcnt(0)
	v_add_f32_e32 v134, v134, v137
	v_xor_b32_e32 v137, 32, v169
	v_cmp_lt_i32_e32 vcc, v137, v144
	s_nop 1
	v_cndmask_b32_e32 v137, v169, v137, vcc
	v_lshlrev_b32_e32 v137, 2, v137
	ds_bpermute_b32 v137, v137, v134
	s_and_saveexec_b64 s[54:55], s[4:5]
	s_cbranch_execz .LBB0_303
	v_lshlrev_b64 v[142:143], 5, v[142:143]
	v_lshl_add_u64 v[142:143], s[68:69], 0, v[142:143]
	s_waitcnt lgkmcnt(0)
	v_add_f32_e32 v134, v134, v137
	global_store_dword v[142:143], v134, off

; __device__ __forceinline__ unsigned cvt_pk_bf16(float lo, float hi) { unsigned r; asm volatile("v_cvt_pk_bf16_f32 %0, %1, %2" : "=v"(r) : "v"(lo), "v"(hi)); return r; }
;     __device__ __forceinline__ void operator()(Acc& acc, const Unit& u, int slot, int cslot, int wr, int wc, int fr, int fq, LAS unsigned char* lds) const {
;     ...
; #pragma unroll
;         for (int ai = 0; ai < 2; ++ai)
; #pragma unroll
;             for (int m = 0; m < 4; ++m) {
;                 const int tr = TROW(ai, m); const size_t row = (size_t)u.pm * BM + tr; const float s = RS[tr]; float ss = 0.f;
;                 bf16_t* rowp = base + row * ld + colt + wc * 32 + 8 * fq;
; #pragma unroll
;                 for (int bj = 0; bj < 2; ++bj) { const f32x4 v0 = acc[ai][bj][m][0] * s, v1 = acc[ai][bj][m][1] * s;
;                     ss += (v0[0] * v0[0] + v0[1] * v0[1]) + (v0[2] * v0[2] + v0[3] * v0[3]) + (v1[0] * v1[0] + v1[1] * v1[1]) + (v1[2] * v1[2] + v1[3] * v1[3]);
;                     u32x4 w; w.x = cvt_pk_bf16(v0[0], v0[1]); w.y = cvt_pk_bf16(v0[2], v0[3]); w.z = cvt_pk_bf16(v1[0], v1[1]); w.w = cvt_pk_bf16(v1[2], v1[3]);
;                     *(u32x4*)(rowp + bj * HALF) = w; }
;                 if (sq) { ss += __shfl_xor(ss, 16); ss += __shfl_xor(ss, 32); if (fq == 0) sq[row * 8 + (pn & 1) * 4 + wc] = ss; }
.LBB0_304:
	ds_read_b32 v158, v170 offset:704
	v_add_u32_e32 v134, 0xb0, v136
	v_lshl_add_u64 v[142:143], s[70:71], 0, v[134:135]
	v_lshlrev_b64 v[144:145], 12, v[142:143]
	v_lshl_add_u64 v[176:177], v[140:141], 0, v[144:145]
	s_waitcnt lgkmcnt(0)
	v_pk_mul_f32 v[140:141], v[16:17], v[158:159] op_sel_hi:[1,0]
	v_pk_mul_f32 v[146:147], v[14:15], v[158:159] op_sel_hi:[1,0]
	v_pk_mul_f32 v[148:149], v[12:13], v[158:159] op_sel_hi:[1,0]
	v_pk_mul_f32 v[144:145], v[10:11], v[158:159] op_sel_hi:[1,0]
	v_cvt_pk_bf16_f32 v150, v146, v147
	v_cvt_pk_bf16_f32 v151, v140, v141
	v_pk_mul_f32 v[154:155], v[6:7], v[158:159] op_sel_hi:[1,0]
	v_cvt_pk_bf16_f32 v152, v144, v145
	v_cvt_pk_bf16_f32 v153, v148, v149
	global_store_dwordx4 v[176:177], v[150:153], off sc1
	v_pk_mul_f32 v[156:157], v[4:5], v[158:159] op_sel_hi:[1,0]
	s_and_b64 vcc, exec, s[6:7]
	v_pk_mul_f32 v[150:151], v[8:9], v[158:159] op_sel_hi:[1,0]
	v_pk_mul_f32 v[152:153], v[2:3], v[158:159] op_sel_hi:[1,0]
	v_cvt_pk_bf16_f32 v172, v154, v155
	v_cvt_pk_bf16_f32 v173, v150, v151
	s_nop 0
	v_cvt_pk_bf16_f32 v174, v152, v153
	v_cvt_pk_bf16_f32 v175, v156, v157
	global_store_dwordx4 v[176:177], v[172:175], off offset:256 sc1
	s_cbranch_vccnz .LBB0_308
	v_mul_f32_e32 v137, v147, v147
	v_mul_f32_e32 v141, v141, v141
	v_fmac_f32_e32 v137, v146, v146
	v_fmac_f32_e32 v141, v140, v140
	v_mul_f32_e32 v140, v145, v145
	v_add_f32_e32 v137, v137, v141
	v_fmac_f32_e32 v140, v144, v144
	v_add_f32_e32 v137, v140, v137
	v_mul_f32_e32 v140, v155, v155
	v_mul_f32_e32 v141, v151, v151
	v_mul_f32_e32 v134, v149, v149
	v_fmac_f32_e32 v140, v154, v154
	v_fmac_f32_e32 v141, v150, v150
	v_fmac_f32_e32 v134, v148, v148
	v_add_f32_e32 v140, v140, v141
	v_mul_f32_e32 v141, v153, v153
	v_add_f32_e32 v134, v134, v137
	v_mul_f32_e32 v137, v157, v157
	v_fmac_f32_e32 v141, v152, v152
	v_fmac_f32_e32 v137, v156, v156
	v_add_f32_e32 v140, v141, v140
	v_add_f32_e32 v137, v137, v140
	v_and_b32_e32 v140, 64, v169
	v_add_f32_e32 v134, v134, v137
	v_xor_b32_e32 v137, 16, v169
	v_add_u32_e32 v140, 64, v140
	v_cmp_lt_i32_e32 vcc, v137, v140
	s_nop 1
	v_cndmask_b32_e32 v137, v169, v137, vcc
	v_lshlrev_b32_e32 v137, 2, v137
	ds_bpermute_b32 v137, v137, v134
	s_waitcnt lgkmcnt(0)
	v_add_f32_e32 v134, v134, v137
	v_xor_b32_e32 v137, 32, v169
	v_cmp_lt_i32_e32 vcc, v137, v140
	s_nop 1
	v_cndmask_b32_e32 v137, v169, v137, vcc
	v_lshlrev_b32_e32 v137, 2, v137
	ds_bpermute_b32 v137, v137, v134
	s_and_saveexec_b64 s[6:7], s[4:5]
	s_cbranch_execz .LBB0_307
	v_lshlrev_b64 v[140:141], 5, v[142:143]
	v_lshl_add_u64 v[140:141], s[68:69], 0, v[140:141]
	s_waitcnt lgkmcnt(0)
	v_add_f32_e32 v134, v134, v137
	global_store_dword v[140:141], v134, off

; __device__ __forceinline__ unsigned cvt_pk_bf16(float lo, float hi) { unsigned r; asm volatile("v_cvt_pk_bf16_f32 %0, %1, %2" : "=v"(r) : "v"(lo), "v"(hi)); return r; }
;     __device__ __forceinline__ void operator()(Acc& acc, const Unit& u, int slot, int cslot, int wr, int wc, int fr, int fq, LAS unsigned char* lds) const {
;     ...
;         if (pn >= 8) {
; #pragma unroll
;             for (int ai = 0; ai < 2; ++ai)
; #pragma unroll
;                 for (int m = 0; m < 4; ++m) {
;                     const int tr = TROW(ai, m); const size_t row = (size_t)u.pm * BM + tr; const float s = RS[tr], s2 = s * s;
;                     const f32x4 v0 = acc[ai][0][m][0] * acc[ai][1][m][0] * s2, v1 = acc[ai][0][m][1] * acc[ai][1][m][1] * s2;
;                     u32x4 w; w.x = cvt_pk_bf16(v0[0], v0[1]); w.y = cvt_pk_bf16(v0[2], v0[3]); w.z = cvt_pk_bf16(v1[0], v1[1]); w.w = cvt_pk_bf16(v1[2], v1[3]);
;                     *(u32x4*)(Gb + row * 2048 + 1024 + (pn - 8) * 128 + wc * 32 + 8 * fq) = w;
;                 }
;             return;
.LBB0_309:
	ds_read_b32 v134, v170
	s_lshl_b32 s4, s22, 7
	s_ashr_i32 s15, s14, 31
	s_add_i32 s22, s4, 0xfffffc00
	v_pk_mul_f32 v[118:119], v[126:127], v[118:119]
	s_waitcnt lgkmcnt(0)
	v_mul_f32_e32 v134, v134, v134
	v_pk_mul_f32 v[116:117], v[124:125], v[116:117]
	v_pk_mul_f32 v[114:115], v[122:123], v[114:115]
	s_lshl_b64 s[4:5], s[14:15], 20
	v_mov_b32_e32 v137, v135
	v_pk_mul_f32 v[120:121], v[128:129], v[120:121]
	v_pk_mul_f32 v[118:119], v[118:119], v[134:135] op_sel_hi:[1,0]
	v_pk_mul_f32 v[122:123], v[116:117], v[134:135] op_sel_hi:[1,0]
	v_pk_mul_f32 v[114:115], v[114:115], v[134:135] op_sel_hi:[1,0]
	s_add_u32 s4, s38, s4
	v_pk_mul_f32 v[120:121], v[120:121], v[134:135] op_sel_hi:[1,0]
	v_cvt_pk_bf16_f32 v116, v118, v119
	s_addc_u32 s5, s39, s5
	v_cvt_pk_bf16_f32 v117, v120, v121
	v_cvt_pk_bf16_f32 v118, v114, v115
	v_cvt_pk_bf16_f32 v119, v122, v123
	v_lshlrev_b64 v[114:115], 12, v[136:137]
	ds_read_b32 v122, v170 offset:64
	v_lshl_add_u64 v[114:115], s[4:5], 0, v[114:115]
	s_lshl_b64 s[6:7], s[22:23], 1
	v_lshl_add_u64 v[114:115], v[114:115], 0, s[6:7]
	s_lshl_b32 s22, s63, 1
	v_lshl_add_u64 v[120:121], v[114:115], 0, s[22:23]
	v_lshlrev_b64 v[114:115], 1, v[138:139]
	v_lshl_add_u64 v[120:121], v[120:121], 0, v[114:115]
	global_store_dwordx4 v[120:121], v[116:119], off offset:2048 sc1
	v_pk_mul_f32 v[104:105], v[112:113], v[104:105]
	v_pk_mul_f32 v[102:103], v[110:111], v[102:103]
	s_waitcnt lgkmcnt(0)
	v_mul_f32_e32 v116, v122, v122
	v_pk_mul_f32 v[100:101], v[108:109], v[100:101]
	v_pk_mul_f32 v[98:99], v[106:107], v[98:99]
	v_or_b32_e32 v134, 16, v136
	v_pk_mul_f32 v[104:105], v[104:105], v[116:117] op_sel_hi:[1,0]
	v_pk_mul_f32 v[102:103], v[102:103], v[116:117] op_sel_hi:[1,0]
	v_pk_mul_f32 v[106:107], v[100:101], v[116:117] op_sel_hi:[1,0]
	v_pk_mul_f32 v[100:101], v[98:99], v[116:117] op_sel_hi:[1,0]
	v_cvt_pk_bf16_f32 v98, v102, v103
	v_cvt_pk_bf16_f32 v99, v104, v105
	v_lshlrev_b64 v[102:103], 12, v[134:135]
	v_cvt_pk_bf16_f32 v100, v100, v101
	v_cvt_pk_bf16_f32 v101, v106, v107
	ds_read_b32 v104, v170 offset:128
	v_lshl_add_u64 v[102:103], s[4:5], 0, v[102:103]
	v_lshl_add_u64 v[102:103], v[102:103], 0, s[6:7]
	v_lshl_add_u64 v[102:103], v[102:103], 0, s[22:23]
	v_lshl_add_u64 v[102:103], v[102:103], 0, v[114:115]
	global_store_dwordx4 v[102:103], v[98:101], off offset:2048 sc1
	v_pk_mul_f32 v[88:89], v[96:97], v[88:89]
	v_pk_mul_f32 v[86:87], v[94:95], v[86:87]
	s_waitcnt lgkmcnt(0)
	v_mul_f32_e32 v98, v104, v104
	v_pk_mul_f32 v[84:85], v[92:93], v[84:85]
	v_pk_mul_f32 v[82:83], v[90:91], v[82:83]
	v_or_b32_e32 v134, 32, v136
	v_pk_mul_f32 v[88:89], v[88:89], v[98:99] op_sel_hi:[1,0]
	v_pk_mul_f32 v[86:87], v[86:87], v[98:99] op_sel_hi:[1,0]
	v_pk_mul_f32 v[90:91], v[84:85], v[98:99] op_sel_hi:[1,0]
	v_pk_mul_f32 v[84:85], v[82:83], v[98:99] op_sel_hi:[1,0]
	v_cvt_pk_bf16_f32 v82, v86, v87
	v_cvt_pk_bf16_f32 v83, v88, v89
	v_lshlrev_b64 v[86:87], 12, v[134:135]
	v_cvt_pk_bf16_f32 v84, v84, v85
	v_cvt_pk_bf16_f32 v85, v90, v91
	ds_read_b32 v88, v170 offset:192
	v_lshl_add_u64 v[86:87], s[4:5], 0, v[86:87]
	v_lshl_add_u64 v[86:87], v[86:87], 0, s[6:7]
	v_lshl_add_u64 v[86:87], v[86:87], 0, s[22:23]
	v_lshl_add_u64 v[86:87], v[86:87], 0, v[114:115]
	global_store_dwordx4 v[86:87], v[82:85], off offset:2048 sc1
	v_pk_mul_f32 v[72:73], v[80:81], v[72:73]
	v_pk_mul_f32 v[70:71], v[78:79], v[70:71]
	s_waitcnt lgkmcnt(0)
	v_mul_f32_e32 v82, v88, v88
	v_pk_mul_f32 v[68:69], v[76:77], v[68:69]
	v_pk_mul_f32 v[66:67], v[74:75], v[66:67]
	v_or_b32_e32 v134, 48, v136
	v_pk_mul_f32 v[72:73], v[72:73], v[82:83] op_sel_hi:[1,0]
	v_pk_mul_f32 v[70:71], v[70:71], v[82:83] op_sel_hi:[1,0]
	v_pk_mul_f32 v[74:75], v[68:69], v[82:83] op_sel_hi:[1,0]
	v_pk_mul_f32 v[68:69], v[66:67], v[82:83] op_sel_hi:[1,0]
	v_cvt_pk_bf16_f32 v66, v70, v71
	v_cvt_pk_bf16_f32 v67, v72, v73
	v_lshlrev_b64 v[70:71], 12, v[134:135]
	v_cvt_pk_bf16_f32 v68, v68, v69
	v_cvt_pk_bf16_f32 v69, v74, v75
	ds_read_b32 v72, v170 offset:512
	v_lshl_add_u64 v[70:71], s[4:5], 0, v[70:71]
	v_lshl_add_u64 v[70:71], v[70:71], 0, s[6:7]
	v_lshl_add_u64 v[70:71], v[70:71], 0, s[22:23]
	v_lshl_add_u64 v[70:71], v[70:71], 0, v[114:115]
	global_store_dwordx4 v[70:71], v[66:69], off offset:2048 sc1
	v_pk_mul_f32 v[56:57], v[64:65], v[56:57]
	v_pk_mul_f32 v[54:55], v[62:63], v[54:55]
	s_waitcnt lgkmcnt(0)
; __device__ __forceinline__ unsigned cvt_pk_bf16(float lo, float hi) { unsigned r; asm volatile("v_cvt_pk_bf16_f32 %0, %1, %2" : "=v"(r) : "v"(lo), "v"(hi)); return r; }
;     __device__ __forceinline__ void operator()(Acc& acc, const Unit& u, int slot, int cslot, int wr, int wc, int fr, int fq, LAS unsigned char* lds) const {
;     ...
;         if (pn >= 8) {
; #pragma unroll
;             for (int ai = 0; ai < 2; ++ai)
; #pragma unroll
;                 for (int m = 0; m < 4; ++m) {
;                     const int tr = TROW(ai, m); const size_t row = (size_t)u.pm * BM + tr; const float s = RS[tr], s2 = s * s;
;                     const f32x4 v0 = acc[ai][0][m][0] * acc[ai][1][m][0] * s2, v1 = acc[ai][0][m][1] * acc[ai][1][m][1] * s2;
;                     u32x4 w; w.x = cvt_pk_bf16(v0[0], v0[1]); w.y = cvt_pk_bf16(v0[2], v0[3]); w.z = cvt_pk_bf16(v1[0], v1[1]); w.w = cvt_pk_bf16(v1[2], v1[3]);
;                     *(u32x4*)(Gb + row * 2048 + 1024 + (pn - 8) * 128 + wc * 32 + 8 * fq) = w;
;                 }
;             return;
	v_mul_f32_e32 v66, v72, v72
	v_pk_mul_f32 v[52:53], v[60:61], v[52:53]
	v_pk_mul_f32 v[50:51], v[58:59], v[50:51]
	v_add_u32_e32 v134, 0x80, v136
	v_pk_mul_f32 v[56:57], v[56:57], v[66:67] op_sel_hi:[1,0]
	v_pk_mul_f32 v[54:55], v[54:55], v[66:67] op_sel_hi:[1,0]
	v_pk_mul_f32 v[58:59], v[52:53], v[66:67] op_sel_hi:[1,0]
	v_pk_mul_f32 v[52:53], v[50:51], v[66:67] op_sel_hi:[1,0]
	v_cvt_pk_bf16_f32 v50, v54, v55
	v_cvt_pk_bf16_f32 v51, v56, v57
	v_lshlrev_b64 v[54:55], 12, v[134:135]
	v_cvt_pk_bf16_f32 v52, v52, v53
	v_cvt_pk_bf16_f32 v53, v58, v59
	ds_read_b32 v56, v170 offset:576
	v_lshl_add_u64 v[54:55], s[4:5], 0, v[54:55]
	v_lshl_add_u64 v[54:55], v[54:55], 0, s[6:7]
	v_lshl_add_u64 v[54:55], v[54:55], 0, s[22:23]
	v_lshl_add_u64 v[54:55], v[54:55], 0, v[114:115]
	global_store_dwordx4 v[54:55], v[50:53], off offset:2048 sc1
	v_pk_mul_f32 v[40:41], v[48:49], v[40:41]
	v_pk_mul_f32 v[38:39], v[46:47], v[38:39]
	s_waitcnt lgkmcnt(0)
	v_mul_f32_e32 v50, v56, v56
	v_pk_mul_f32 v[36:37], v[44:45], v[36:37]
	v_pk_mul_f32 v[34:35], v[42:43], v[34:35]
	v_add_u32_e32 v134, 0x90, v136
	v_pk_mul_f32 v[40:41], v[40:41], v[50:51] op_sel_hi:[1,0]
	v_pk_mul_f32 v[38:39], v[38:39], v[50:51] op_sel_hi:[1,0]
	v_pk_mul_f32 v[42:43], v[36:37], v[50:51] op_sel_hi:[1,0]
	v_pk_mul_f32 v[36:37], v[34:35], v[50:51] op_sel_hi:[1,0]
	v_cvt_pk_bf16_f32 v34, v38, v39
	v_cvt_pk_bf16_f32 v35, v40, v41
	v_lshlrev_b64 v[38:39], 12, v[134:135]
	v_cvt_pk_bf16_f32 v36, v36, v37
	v_cvt_pk_bf16_f32 v37, v42, v43
	ds_read_b32 v40, v170 offset:640
	v_lshl_add_u64 v[38:39], s[4:5], 0, v[38:39]
	v_lshl_add_u64 v[38:39], v[38:39], 0, s[6:7]
	v_lshl_add_u64 v[38:39], v[38:39], 0, s[22:23]
	v_lshl_add_u64 v[38:39], v[38:39], 0, v[114:115]
	global_store_dwordx4 v[38:39], v[34:37], off offset:2048 sc1
	v_pk_mul_f32 v[24:25], v[32:33], v[24:25]
	v_pk_mul_f32 v[22:23], v[30:31], v[22:23]
	s_waitcnt lgkmcnt(0)
	v_mul_f32_e32 v34, v40, v40
	v_pk_mul_f32 v[20:21], v[28:29], v[20:21]
	v_pk_mul_f32 v[18:19], v[26:27], v[18:19]
	v_add_u32_e32 v134, 0xa0, v136
	v_pk_mul_f32 v[24:25], v[24:25], v[34:35] op_sel_hi:[1,0]
	v_pk_mul_f32 v[22:23], v[22:23], v[34:35] op_sel_hi:[1,0]
	v_pk_mul_f32 v[26:27], v[20:21], v[34:35] op_sel_hi:[1,0]
	v_pk_mul_f32 v[20:21], v[18:19], v[34:35] op_sel_hi:[1,0]
	v_cvt_pk_bf16_f32 v18, v22, v23
	v_cvt_pk_bf16_f32 v19, v24, v25
	v_lshlrev_b64 v[22:23], 12, v[134:135]
	v_cvt_pk_bf16_f32 v20, v20, v21
	v_cvt_pk_bf16_f32 v21, v26, v27
	ds_read_b32 v24, v170 offset:704
	v_lshl_add_u64 v[22:23], s[4:5], 0, v[22:23]
	v_lshl_add_u64 v[22:23], v[22:23], 0, s[6:7]
	v_lshl_add_u64 v[22:23], v[22:23], 0, s[22:23]
	v_lshl_add_u64 v[22:23], v[22:23], 0, v[114:115]
	global_store_dwordx4 v[22:23], v[18:21], off offset:2048 sc1
	v_pk_mul_f32 v[6:7], v[14:15], v[6:7]
	v_add_u32_e32 v134, 0xb0, v136
	s_waitcnt lgkmcnt(0)
	v_mul_f32_e32 v18, v24, v24
	v_pk_mul_f32 v[6:7], v[6:7], v[18:19] op_sel_hi:[1,0]
	v_pk_mul_f32 v[4:5], v[12:13], v[4:5]
	v_pk_mul_f32 v[2:3], v[10:11], v[2:3]
	v_pk_mul_f32 v[10:11], v[4:5], v[18:19] op_sel_hi:[1,0]
	v_pk_mul_f32 v[4:5], v[2:3], v[18:19] op_sel_hi:[1,0]
	v_cvt_pk_bf16_f32 v2, v6, v7
	v_lshlrev_b64 v[6:7], 12, v[134:135]
	v_lshl_add_u64 v[6:7], s[4:5], 0, v[6:7]
	v_lshl_add_u64 v[6:7], v[6:7], 0, s[6:7]
	v_lshl_add_u64 v[6:7], v[6:7], 0, s[22:23]
	v_pk_mul_f32 v[8:9], v[16:17], v[8:9]
	v_lshl_add_u64 v[6:7], v[6:7], 0, v[114:115]
	v_pk_mul_f32 v[8:9], v[8:9], v[18:19] op_sel_hi:[1,0]
	s_nop 0
	v_cvt_pk_bf16_f32 v3, v8, v9
	v_cvt_pk_bf16_f32 v4, v4, v5
	v_cvt_pk_bf16_f32 v5, v10, v11
	global_store_dwordx4 v[6:7], v[2:5], off offset:2048 sc1
	s_and_b64 vcc, exec, s[8:9]
	s_mov_b64 s[4:5], -1
	s_cbranch_vccnz .LBB0_260

;     __device__ __forceinline__ void operator()(Acc& acc, const Unit& u, int slot, int cslot, int wr, int wc, int fr, int fq, LAS unsigned char* lds) const {
;     ...
;         for (int n = 0; n < 2; ++n) {
;             f32x4 w0[2], w1[2], w2[2], bb[2];
; #pragma unroll
;             for (int bj = 0; bj < 2; ++bj) { const LAS float* cwl = (const LAS float*)(lds + CWB_OFF + cslot * 4096) + bj * 128 + lcol + 4 * n;
;                 w0[bj] = *(const LAS f32x4*)(cwl); w1[bj] = *(const LAS f32x4*)(cwl + 256); w2[bj] = *(const LAS f32x4*)(cwl + 512); bb[bj] = *(const LAS f32x4*)(cwl + 768); }
; #pragma unroll
;             for (int ai = 0; ai < 2; ++ai) { const int blk = 2 * ai + wr;
;                 f32x4 pu[2], pd[2];
; #pragma unroll
;                 for (int bj = 0; bj < 2; ++bj) {
;                     f32x4 hu = (f32x4){0.f, 0.f, 0.f, 0.f}, hd = (f32x4){0.f, 0.f, 0.f, 0.f};
;                     if (blk > 0) hu = *(const LAS f32x4*)(XR + (2 * blk - 1) * 256 + bj * HALF + lcol + 4 * n);
;                     if (blk < 3) hd = *(const LAS f32x4*)(XR + (2 * blk + 2) * 256 + bj * HALF + lcol + 4 * n);
;                     pu[bj] = hu; pd[bj] = hd;
;                     dpp_shr1_keep4(pu[bj], acc[ai][bj][3][n]); dpp_shl1_keep4(pd[bj], acc[ai][bj][0][n]);
;                 }
; #pragma unroll
;                 for (int m = 0; m < 4; ++m) {
;                     f32x2 uu[2][2];
; #pragma unroll
;                     for (int bj = 0; bj < 2; ++bj) {
;                         const f32x4 cur = acc[ai][bj][m][n];
;                         const f32x4 up = (m > 0) ? acc[ai][bj][m > 0 ? m - 1 : 0][n] : pu[bj];
;                         const f32x4 dn = (m < 3) ? acc[ai][bj][m < 3 ? m + 1 : 3][n] : pd[bj];
; #pragma unroll
;                         for (int h = 0; h < 2; ++h) {
;                             const f32x2 c2 = {cur[2 * h], cur[2 * h + 1]}, u2 = {up[2 * h], up[2 * h + 1]}, d2 = {dn[2 * h], dn[2 * h + 1]};
;                             const f32x2 k0 = {w0[bj][2 * h], w0[bj][2 * h + 1]}, k1 = {w1[bj][2 * h], w1[bj][2 * h + 1]}, k2 = {w2[bj][2 * h], w2[bj][2 * h + 1]}, b2 = {bb[bj][2 * h], bb[bj][2 * h + 1]};
;                             uu[bj][h] = k0 * u2 + (k1 * c2 + (k2 * d2 + b2));
;                         }
;                     }
;                     f32x4 r;
; #pragma unroll
;                     for (int h = 0; h < 2; ++h) {
.LBB0_1005:
	s_waitcnt lgkmcnt(0)
	v_pk_fma_f32 v[138:139], v[84:85], v[108:109], v[112:113]
	v_pk_fma_f32 v[140:141], v[82:83], v[106:107], v[110:111]
	v_pk_fma_f32 v[138:139], v[72:73], v[104:105], v[138:139]
	v_pk_fma_f32 v[140:141], v[70:71], v[102:103], v[140:141]
	v_pk_fma_f32 v[130:131], v[92:93], v[130:131], v[138:139]
	v_pk_fma_f32 v[120:121], v[90:91], v[120:121], v[140:141]
	s_waitcnt lgkmcnt(0)
	v_pk_fma_f32 v[138:139], v[88:89], v[96:97], v[100:101]
	v_pk_fma_f32 v[140:141], v[86:87], v[94:95], v[98:99]
	s_nop 1
	v_mov_b32_dpp v122, v58 row_shr:1 row_mask:0xf bank_mask:0xf
	v_mov_b32_dpp v123, v59 row_shr:1 row_mask:0xf bank_mask:0xf
	v_mov_b32_dpp v136, v60 row_shr:1 row_mask:0xf bank_mask:0xf
	v_mov_b32_dpp v115, v61 row_shr:1 row_mask:0xf bank_mask:0xf
	v_pk_fma_f32 v[138:139], v[68:69], v[80:81], v[138:139]
	v_pk_fma_f32 v[140:141], v[66:67], v[78:79], v[140:141]
	v_mov_b32_e32 v137, v115
	v_pk_fma_f32 v[122:123], v[74:75], v[122:123], v[140:141]
	v_exp_f32_e32 v140, v120
	v_exp_f32_e32 v141, v121
	v_pk_fma_f32 v[136:137], v[76:77], v[136:137], v[138:139]
	v_exp_f32_e32 v138, v130
	v_exp_f32_e32 v139, v131
	v_pk_add_f32 v[140:141], v[140:141], 1.0 op_sel_hi:[1,0]
	v_lshl_or_b32 v124, v186, 2, s72
	v_rcp_f32_e32 v140, v140
	v_pk_add_f32 v[138:139], v[138:139], 1.0 op_sel_hi:[1,0]
	v_rcp_f32_e32 v141, v141
	v_rcp_f32_e32 v138, v138
	v_rcp_f32_e32 v139, v139
	v_lshl_add_u32 v118, s62, 7, v194
	s_ashr_i32 s43, s42, 31
	v_ashrrev_i32_e32 v119, 31, v118
	v_pk_mul_f32 v[120:121], v[120:121], v[122:123]
	v_pk_mul_f32 v[122:123], v[130:131], v[136:137]
	v_cmp_ne_u32_e32 vcc, 0, v124
	s_nop 1
	v_mov_b32_dpp v116, v66 row_shl:1 row_mask:0xf bank_mask:0xf
	v_mov_b32_dpp v117, v67 row_shl:1 row_mask:0xf bank_mask:0xf
	v_mov_b32_dpp v132, v68 row_shl:1 row_mask:0xf bank_mask:0xf
	v_mov_b32_dpp v133, v69 row_shl:1 row_mask:0xf bank_mask:0xf
	v_pk_mul_f32 v[120:121], v[140:141], v[120:121]
	v_pk_mul_f32 v[122:123], v[138:139], v[122:123]
	v_cvt_pk_bf16_f32 v136, v120, v121
	s_nop 0
	v_cvt_pk_bf16_f32 v137, v122, v123
	s_and_saveexec_b64 s[8:9], vcc
	s_xor_b64 s[8:9], exec, s[8:9]
	s_cbranch_execz .LBB0_1007
	s_lshl_b64 s[6:7], s[42:43], 8
	v_mov_b32_e32 v125, v187
	v_lshl_add_u64 v[120:121], s[6:7], 0, v[124:125]
	v_mov_b64_e32 v[122:123], s[12:13]
	v_mad_u64_u32 v[122:123], s[54:55], v120, s40, v[122:123]
	v_mad_i32_i24 v123, v121, s40, v123
	v_lshl_add_u64 v[120:121], v[118:119], 1, v[122:123]
	global_store_dwordx4 v[120:121], v[134:137], off sc1
;     __device__ __forceinline__ void operator()(Acc& acc, const Unit& u, int slot, int cslot, int wr, int wc, int fr, int fq, LAS unsigned char* lds) const {
;     ...
;         for (int n = 0; n < 2; ++n) {
;             f32x4 w0[2], w1[2], w2[2], bb[2];
; #pragma unroll
;             for (int bj = 0; bj < 2; ++bj) { const LAS float* cwl = (const LAS float*)(lds + CWB_OFF + cslot * 4096) + bj * 128 + lcol + 4 * n;
;                 w0[bj] = *(const LAS f32x4*)(cwl); w1[bj] = *(const LAS f32x4*)(cwl + 256); w2[bj] = *(const LAS f32x4*)(cwl + 512); bb[bj] = *(const LAS f32x4*)(cwl + 768); }
; #pragma unroll
;             for (int ai = 0; ai < 2; ++ai) { const int blk = 2 * ai + wr;
;                 f32x4 pu[2], pd[2];
; #pragma unroll
;                 for (int bj = 0; bj < 2; ++bj) {
;                     f32x4 hu = (f32x4){0.f, 0.f, 0.f, 0.f}, hd = (f32x4){0.f, 0.f, 0.f, 0.f};
;                     if (blk > 0) hu = *(const LAS f32x4*)(XR + (2 * blk - 1) * 256 + bj * HALF + lcol + 4 * n);
;                     if (blk < 3) hd = *(const LAS f32x4*)(XR + (2 * blk + 2) * 256 + bj * HALF + lcol + 4 * n);
;                     pu[bj] = hu; pd[bj] = hd;
;                     dpp_shr1_keep4(pu[bj], acc[ai][bj][3][n]); dpp_shl1_keep4(pd[bj], acc[ai][bj][0][n]);
;                 }
; #pragma unroll
;                 for (int m = 0; m < 4; ++m) {
;                     f32x2 uu[2][2];
; #pragma unroll
;                     for (int bj = 0; bj < 2; ++bj) {
;                         const f32x4 cur = acc[ai][bj][m][n];
;                         const f32x4 up = (m > 0) ? acc[ai][bj][m > 0 ? m - 1 : 0][n] : pu[bj];
;                         const f32x4 dn = (m < 3) ? acc[ai][bj][m < 3 ? m + 1 : 3][n] : pd[bj];
; #pragma unroll
;                         for (int h = 0; h < 2; ++h) {
;                             const f32x2 c2 = {cur[2 * h], cur[2 * h + 1]}, u2 = {up[2 * h], up[2 * h + 1]}, d2 = {dn[2 * h], dn[2 * h + 1]};
;                             const f32x2 k0 = {w0[bj][2 * h], w0[bj][2 * h + 1]}, k1 = {w1[bj][2 * h], w1[bj][2 * h + 1]}, k2 = {w2[bj][2 * h], w2[bj][2 * h + 1]}, b2 = {bb[bj][2 * h], bb[bj][2 * h + 1]};
;                             uu[bj][h] = k0 * u2 + (k1 * c2 + (k2 * d2 + b2));
;                         }
;                     }
;                     f32x4 r;
; #pragma unroll
;                     for (int h = 0; h < 2; ++h) {
.LBB0_1007:
	s_or_saveexec_b64 s[8:9], s[8:9]
	v_mov_b64_e32 v[120:121], s[6:7]
	s_xor_b64 exec, exec, s[8:9]
	s_lshl_b64 s[6:7], s[42:43], 8
	v_mov_b64_e32 v[120:121], s[6:7]
	s_or_b64 exec, exec, s[8:9]
	v_mov_b32_e32 v122, v64
	v_mov_b32_e32 v123, v64
	v_mov_b32_e32 v65, v64
	v_pk_mul_f32 v[14:15], v[14:15], v[122:123]
	v_pk_mul_f32 v[16:17], v[16:17], v[64:65]
	v_pk_mul_f32 v[10:11], v[10:11], v[122:123]
	v_pk_fma_f32 v[122:123], v[14:15], v[106:107], v[110:111]
	v_pk_mul_f32 v[12:13], v[12:13], v[64:65]
	v_pk_fma_f32 v[64:65], v[16:17], v[108:109], v[112:113]
	v_pk_fma_f32 v[122:123], v[82:83], v[102:103], v[122:123]
	v_pk_fma_f32 v[64:65], v[84:85], v[104:105], v[64:65]
	v_pk_fma_f32 v[70:71], v[70:71], v[90:91], v[122:123]
	v_pk_fma_f32 v[122:123], v[10:11], v[94:95], v[98:99]
	v_pk_fma_f32 v[64:65], v[72:73], v[92:93], v[64:65]
	v_pk_fma_f32 v[72:73], v[12:13], v[96:97], v[100:101]
	v_pk_fma_f32 v[122:123], v[86:87], v[78:79], v[122:123]
	v_pk_fma_f32 v[72:73], v[88:89], v[80:81], v[72:73]
	v_pk_fma_f32 v[66:67], v[66:67], v[74:75], v[122:123]
	v_exp_f32_e32 v122, v64
	v_exp_f32_e32 v123, v65
	v_pk_fma_f32 v[68:69], v[68:69], v[76:77], v[72:73]
	v_exp_f32_e32 v72, v70
	v_exp_f32_e32 v73, v71
	v_pk_add_f32 v[122:123], v[122:123], 1.0 op_sel_hi:[1,0]
	v_pk_mul_f32 v[64:65], v[64:65], v[68:69]
	v_rcp_f32_e32 v122, v122
	v_pk_add_f32 v[72:73], v[72:73], 1.0 op_sel_hi:[1,0]
	v_rcp_f32_e32 v123, v123
	v_rcp_f32_e32 v72, v72
	v_rcp_f32_e32 v73, v73
	v_pk_mul_f32 v[66:67], v[70:71], v[66:67]
	v_pk_mul_f32 v[64:65], v[64:65], v[122:123]
	v_or_b32_e32 v186, 1, v124
	v_pk_mul_f32 v[66:67], v[66:67], v[72:73]
	v_mov_b64_e32 v[68:69], s[12:13]
	v_cvt_pk_bf16_f32 v130, v66, v67
	v_cvt_pk_bf16_f32 v131, v64, v65
	v_lshl_add_u64 v[64:65], v[120:121], 0, v[186:187]
	v_mad_u64_u32 v[70:71], s[6:7], v64, s40, v[68:69]
	v_mov_b32_e32 v64, v71
	v_mad_u64_u32 v[64:65], s[6:7], v65, s40, v[64:65]
	v_mov_b32_e32 v71, v64
	v_lshlrev_b64 v[66:67], 1, v[118:119]
	v_lshl_add_u64 v[64:65], v[70:71], 0, v[66:67]
	v_pk_fma_f32 v[70:71], v[54:55], v[106:107], v[110:111]
	global_store_dwordx4 v[64:65], v[128:131], off sc1
	v_pk_fma_f32 v[64:65], v[56:57], v[108:109], v[112:113]
	v_pk_fma_f32 v[70:71], v[14:15], v[102:103], v[70:71]
	v_pk_fma_f32 v[64:65], v[16:17], v[104:105], v[64:65]
	v_pk_fma_f32 v[70:71], v[82:83], v[90:91], v[70:71]
	v_pk_fma_f32 v[82:83], v[58:59], v[94:95], v[98:99]
	v_pk_fma_f32 v[64:65], v[84:85], v[92:93], v[64:65]
	v_pk_fma_f32 v[82:83], v[10:11], v[78:79], v[82:83]
	v_exp_f32_e32 v84, v70
	v_pk_fma_f32 v[82:83], v[86:87], v[74:75], v[82:83]
	v_exp_f32_e32 v86, v64
	v_exp_f32_e32 v87, v65
	v_exp_f32_e32 v85, v71
	v_pk_fma_f32 v[72:73], v[60:61], v[96:97], v[100:101]
	v_pk_mul_f32 v[70:71], v[70:71], v[82:83]
	v_pk_add_f32 v[86:87], v[86:87], 1.0 op_sel_hi:[1,0]
	v_pk_add_f32 v[84:85], v[84:85], 1.0 op_sel_hi:[1,0]
	v_rcp_f32_e32 v86, v86
	v_rcp_f32_e32 v87, v87
	v_pk_fma_f32 v[72:73], v[12:13], v[80:81], v[72:73]
	v_rcp_f32_e32 v84, v84
	v_rcp_f32_e32 v85, v85
	v_pk_fma_f32 v[72:73], v[88:89], v[76:77], v[72:73]
	v_or_b32_e32 v186, 2, v124
	v_pk_mul_f32 v[64:65], v[64:65], v[72:73]
	v_pk_mul_f32 v[70:71], v[70:71], v[84:85]
	v_pk_mul_f32 v[64:65], v[64:65], v[86:87]
	v_cvt_pk_bf16_f32 v128, v70, v71
	v_mov_b32_e32 v115, v45
	v_cvt_pk_bf16_f32 v129, v64, v65
	v_lshl_add_u64 v[64:65], v[120:121], 0, v[186:187]
	v_mad_u64_u32 v[68:69], s[6:7], v64, s40, v[68:69]
	v_mov_b32_e32 v64, v69
	v_mov_b32_e32 v45, v26
	v_mad_u64_u32 v[64:65], s[6:7], v65, s40, v[64:65]
	v_pk_fma_f32 v[44:45], v[108:109], v[44:45], v[112:113]
	v_mov_b32_e32 v69, v64
	v_pk_fma_f32 v[44:45], v[56:57], v[104:105], v[44:45]
	v_lshl_add_u64 v[64:65], v[68:69], 0, v[66:67]
	v_pk_fma_f32 v[16:17], v[16:17], v[92:93], v[44:45]
	v_pk_fma_f32 v[44:45], v[94:95], v[116:117], v[98:99]
	global_store_dwordx4 v[64:65], v[126:129], off sc1
	v_pk_fma_f32 v[64:65], v[106:107], v[114:115], v[110:111]
	v_pk_fma_f32 v[44:45], v[58:59], v[78:79], v[44:45]
	v_pk_fma_f32 v[54:55], v[54:55], v[102:103], v[64:65]
	v_pk_fma_f32 v[10:11], v[10:11], v[74:75], v[44:45]
	v_pk_fma_f32 v[44:45], v[96:97], v[132:133], v[100:101]
	v_pk_fma_f32 v[14:15], v[14:15], v[90:91], v[54:55]
	v_pk_fma_f32 v[44:45], v[60:61], v[80:81], v[44:45]
	v_exp_f32_e32 v54, v14
	v_exp_f32_e32 v55, v15
	v_pk_fma_f32 v[12:13], v[12:13], v[76:77], v[44:45]
	v_exp_f32_e32 v44, v16
	v_exp_f32_e32 v45, v17
	v_pk_add_f32 v[54:55], v[54:55], 1.0 op_sel_hi:[1,0]
	s_movk_i32 s6, 0xfc
	v_rcp_f32_e32 v54, v54
	v_pk_add_f32 v[44:45], v[44:45], 1.0 op_sel_hi:[1,0]
	v_rcp_f32_e32 v55, v55
	v_rcp_f32_e32 v44, v44
	v_rcp_f32_e32 v45, v45
	v_pk_mul_f32 v[10:11], v[14:15], v[10:11]
	v_pk_mul_f32 v[12:13], v[16:17], v[12:13]
	v_cmp_ne_u32_e32 vcc, s6, v124
	v_pk_mul_f32 v[10:11], v[54:55], v[10:11]
	v_pk_mul_f32 v[12:13], v[44:45], v[12:13]
	v_cvt_pk_bf16_f32 v64, v10, v11
	s_nop 0
	v_cvt_pk_bf16_f32 v65, v12, v13
	s_and_saveexec_b64 s[6:7], vcc
	s_cbranch_execz .LBB0_1011
	v_or_b32_e32 v186, 3, v124
	v_lshl_add_u64 v[10:11], v[120:121], 0, v[186:187]
	v_mov_b64_e32 v[12:13], s[12:13]
	v_mad_u64_u32 v[12:13], s[8:9], v10, s40, v[12:13]
	v_mov_b32_e32 v10, v13
	v_mad_u64_u32 v[10:11], s[8:9], v11, s40, v[10:11]
	v_mov_b32_e32 v13, v10
	v_lshl_add_u64 v[10:11], v[118:119], 1, v[12:13]
	global_store_dwordx4 v[10:11], v[62:65], off sc1

;     __device__ __forceinline__ void operator()(Acc& acc, const Unit& u, int slot, int cslot, int wr, int wc, int fr, int fq, LAS unsigned char* lds) const {
;     ...
;         for (int n = 0; n < 2; ++n) {
;             f32x4 w0[2], w1[2], w2[2], bb[2];
; #pragma unroll
;             for (int bj = 0; bj < 2; ++bj) { const LAS float* cwl = (const LAS float*)(lds + CWB_OFF + cslot * 4096) + bj * 128 + lcol + 4 * n;
;                 w0[bj] = *(const LAS f32x4*)(cwl); w1[bj] = *(const LAS f32x4*)(cwl + 256); w2[bj] = *(const LAS f32x4*)(cwl + 512); bb[bj] = *(const LAS f32x4*)(cwl + 768); }
; #pragma unroll
;             for (int ai = 0; ai < 2; ++ai) { const int blk = 2 * ai + wr;
;                 f32x4 pu[2], pd[2];
; #pragma unroll
;                 for (int bj = 0; bj < 2; ++bj) {
;                     f32x4 hu = (f32x4){0.f, 0.f, 0.f, 0.f}, hd = (f32x4){0.f, 0.f, 0.f, 0.f};
;                     if (blk > 0) hu = *(const LAS f32x4*)(XR + (2 * blk - 1) * 256 + bj * HALF + lcol + 4 * n);
;                     if (blk < 3) hd = *(const LAS f32x4*)(XR + (2 * blk + 2) * 256 + bj * HALF + lcol + 4 * n);
;                     pu[bj] = hu; pd[bj] = hd;
;                     dpp_shr1_keep4(pu[bj], acc[ai][bj][3][n]); dpp_shl1_keep4(pd[bj], acc[ai][bj][0][n]);
;                 }
; #pragma unroll
;                 for (int m = 0; m < 4; ++m) {
;                     f32x2 uu[2][2];
; #pragma unroll
;                     for (int bj = 0; bj < 2; ++bj) {
;                         const f32x4 cur = acc[ai][bj][m][n];
;                         const f32x4 up = (m > 0) ? acc[ai][bj][m > 0 ? m - 1 : 0][n] : pu[bj];
;                         const f32x4 dn = (m < 3) ? acc[ai][bj][m < 3 ? m + 1 : 3][n] : pd[bj];
; #pragma unroll
;                         for (int h = 0; h < 2; ++h) {
;                             const f32x2 c2 = {cur[2 * h], cur[2 * h + 1]}, u2 = {up[2 * h], up[2 * h + 1]}, d2 = {dn[2 * h], dn[2 * h + 1]};
;                             const f32x2 k0 = {w0[bj][2 * h], w0[bj][2 * h + 1]}, k1 = {w1[bj][2 * h], w1[bj][2 * h + 1]}, k2 = {w2[bj][2 * h], w2[bj][2 * h + 1]}, b2 = {bb[bj][2 * h], bb[bj][2 * h + 1]};
;                             uu[bj][h] = k0 * u2 + (k1 * c2 + (k2 * d2 + b2));
;                         }
;                     }
;                     f32x4 r;
; #pragma unroll
;                     for (int h = 0; h < 2; ++h) {
.LBB0_1015:
	v_mov_b32_e32 v26, v27
	v_mov_b32_e32 v60, v27
	v_mov_b32_e32 v61, v27
	v_pk_mul_f32 v[8:9], v[8:9], v[60:61]
	v_pk_mul_f32 v[6:7], v[6:7], v[26:27]
	v_pk_mul_f32 v[4:5], v[4:5], v[60:61]
	v_pk_mul_f32 v[2:3], v[2:3], v[26:27]
	s_waitcnt lgkmcnt(0)
	v_mov_b32_e32 v27, v57
	v_mov_b32_e32 v26, v56
	v_pk_fma_f32 v[56:57], v[8:9], v[108:109], v[112:113]
	v_pk_fma_f32 v[60:61], v[6:7], v[106:107], v[110:111]
	v_pk_fma_f32 v[56:57], v[32:33], v[104:105], v[56:57]
	v_pk_fma_f32 v[60:61], v[30:31], v[102:103], v[60:61]
	v_pk_fma_f32 v[44:45], v[92:93], v[44:45], v[56:57]
	v_pk_fma_f32 v[54:55], v[90:91], v[54:55], v[60:61]
	v_pk_fma_f32 v[56:57], v[4:5], v[96:97], v[100:101]
	v_pk_fma_f32 v[60:61], v[2:3], v[94:95], v[98:99]
	s_nop 1
	v_mov_b32_dpp v26, v22 row_shr:1 row_mask:0xf bank_mask:0xf
	v_mov_b32_dpp v27, v23 row_shr:1 row_mask:0xf bank_mask:0xf
	v_mov_b32_dpp v58, v24 row_shr:1 row_mask:0xf bank_mask:0xf
	v_mov_b32_dpp v59, v25 row_shr:1 row_mask:0xf bank_mask:0xf
	v_pk_fma_f32 v[56:57], v[36:37], v[80:81], v[56:57]
	v_pk_fma_f32 v[60:61], v[34:35], v[78:79], v[60:61]
	v_pk_fma_f32 v[56:57], v[76:77], v[58:59], v[56:57]
	v_pk_fma_f32 v[26:27], v[74:75], v[26:27], v[60:61]
	v_exp_f32_e32 v60, v54
	v_exp_f32_e32 v61, v55
	v_exp_f32_e32 v58, v44
	v_exp_f32_e32 v59, v45
	v_pk_mul_f32 v[26:27], v[54:55], v[26:27]
	v_pk_add_f32 v[60:61], v[60:61], 1.0 op_sel_hi:[1,0]
	v_pk_mul_f32 v[44:45], v[44:45], v[56:57]
	v_pk_add_f32 v[58:59], v[58:59], 1.0 op_sel_hi:[1,0]
	v_rcp_f32_e32 v60, v60
	v_rcp_f32_e32 v61, v61
	v_rcp_f32_e32 v58, v58
	v_rcp_f32_e32 v59, v59
	v_add_u32_e32 v186, 0x80, v124
	v_pk_mul_f32 v[26:27], v[60:61], v[26:27]
	s_nop 1
	v_mov_b32_dpp v10, v34 row_shl:1 row_mask:0xf bank_mask:0xf
	v_mov_b32_dpp v11, v35 row_shl:1 row_mask:0xf bank_mask:0xf
	v_mov_b32_dpp v12, v36 row_shl:1 row_mask:0xf bank_mask:0xf
	v_mov_b32_dpp v13, v37 row_shl:1 row_mask:0xf bank_mask:0xf
	v_pk_mul_f32 v[54:55], v[58:59], v[44:45]
	v_cvt_pk_bf16_f32 v44, v26, v27
	v_lshl_add_u64 v[26:27], v[120:121], 0, v[186:187]
	v_cvt_pk_bf16_f32 v45, v54, v55
	v_mov_b64_e32 v[54:55], s[12:13]
	v_mad_u64_u32 v[56:57], s[6:7], v26, s40, v[54:55]
	v_mov_b32_e32 v26, v57
	v_mad_u64_u32 v[26:27], s[6:7], v27, s40, v[26:27]
	v_mov_b32_e32 v57, v26
	v_lshl_add_u64 v[26:27], v[56:57], 0, v[66:67]
	global_store_dwordx4 v[26:27], v[42:45], off sc1
	v_pk_fma_f32 v[26:27], v[48:49], v[108:109], v[112:113]
	v_add_u32_e32 v186, 0x81, v124
	v_pk_fma_f32 v[42:43], v[46:47], v[106:107], v[110:111]
	v_pk_fma_f32 v[26:27], v[8:9], v[104:105], v[26:27]
	v_pk_fma_f32 v[42:43], v[6:7], v[102:103], v[42:43]
	v_pk_fma_f32 v[26:27], v[32:33], v[92:93], v[26:27]
	v_pk_fma_f32 v[30:31], v[30:31], v[90:91], v[42:43]
	v_pk_fma_f32 v[42:43], v[50:51], v[94:95], v[98:99]
	v_pk_fma_f32 v[32:33], v[52:53], v[96:97], v[100:101]
	v_pk_fma_f32 v[42:43], v[2:3], v[78:79], v[42:43]
	v_pk_fma_f32 v[32:33], v[4:5], v[80:81], v[32:33]
	v_pk_fma_f32 v[34:35], v[34:35], v[74:75], v[42:43]
	v_exp_f32_e32 v42, v26
	v_exp_f32_e32 v43, v27
	v_pk_fma_f32 v[32:33], v[36:37], v[76:77], v[32:33]
	v_exp_f32_e32 v36, v30
	v_exp_f32_e32 v37, v31
	v_pk_add_f32 v[42:43], v[42:43], 1.0 op_sel_hi:[1,0]
	v_pk_mul_f32 v[26:27], v[26:27], v[32:33]
	v_rcp_f32_e32 v42, v42
	v_pk_add_f32 v[36:37], v[36:37], 1.0 op_sel_hi:[1,0]
	v_rcp_f32_e32 v43, v43
	v_rcp_f32_e32 v36, v36
	v_rcp_f32_e32 v37, v37
	v_pk_mul_f32 v[30:31], v[30:31], v[34:35]
	v_pk_mul_f32 v[26:27], v[26:27], v[42:43]
	v_pk_mul_f32 v[30:31], v[30:31], v[36:37]
	s_nop 0
	v_cvt_pk_bf16_f32 v42, v30, v31
	v_cvt_pk_bf16_f32 v43, v26, v27
	v_lshl_add_u64 v[26:27], v[120:121], 0, v[186:187]
	v_mad_u64_u32 v[30:31], s[6:7], v26, s40, v[54:55]
	v_mov_b32_e32 v26, v31
	v_mad_u64_u32 v[26:27], s[6:7], v27, s40, v[26:27]
	v_mov_b32_e32 v31, v26
	v_lshl_add_u64 v[26:27], v[30:31], 0, v[66:67]
	global_store_dwordx4 v[26:27], v[40:43], off sc1
	v_pk_fma_f32 v[26:27], v[20:21], v[108:109], v[112:113]
	v_pk_fma_f32 v[30:31], v[18:19], v[106:107], v[110:111]
	v_pk_fma_f32 v[26:27], v[48:49], v[104:105], v[26:27]
	v_pk_fma_f32 v[30:31], v[46:47], v[102:103], v[30:31]
	v_pk_fma_f32 v[8:9], v[8:9], v[92:93], v[26:27]
	v_pk_fma_f32 v[26:27], v[24:25], v[96:97], v[100:101]
	v_pk_fma_f32 v[6:7], v[6:7], v[90:91], v[30:31]
	v_pk_fma_f32 v[30:31], v[22:23], v[94:95], v[98:99]
	v_pk_fma_f32 v[26:27], v[52:53], v[80:81], v[26:27]
	v_pk_fma_f32 v[30:31], v[50:51], v[78:79], v[30:31]
	v_pk_fma_f32 v[4:5], v[4:5], v[76:77], v[26:27]
	v_exp_f32_e32 v26, v6
	v_exp_f32_e32 v27, v7
	v_pk_fma_f32 v[2:3], v[2:3], v[74:75], v[30:31]
	v_exp_f32_e32 v30, v8
	v_exp_f32_e32 v31, v9
	v_pk_add_f32 v[26:27], v[26:27], 1.0 op_sel_hi:[1,0]
	v_pk_mul_f32 v[2:3], v[6:7], v[2:3]
	v_rcp_f32_e32 v26, v26
	v_rcp_f32_e32 v27, v27
	v_pk_add_f32 v[30:31], v[30:31], 1.0 op_sel_hi:[1,0]
	v_pk_mul_f32 v[4:5], v[8:9], v[4:5]
	v_rcp_f32_e32 v30, v30
	v_rcp_f32_e32 v31, v31
	v_pk_mul_f32 v[2:3], v[2:3], v[26:27]
	v_add_u32_e32 v186, 0x82, v124
	v_cvt_pk_bf16_f32 v40, v2, v3
	v_pk_mul_f32 v[4:5], v[4:5], v[30:31]
	v_lshl_add_u64 v[2:3], v[120:121], 0, v[186:187]
	v_cvt_pk_bf16_f32 v41, v4, v5
	v_mad_u64_u32 v[4:5], s[6:7], v2, s40, v[54:55]
	v_mov_b32_e32 v2, v5
	v_mad_u64_u32 v[2:3], s[6:7], v3, s40, v[2:3]
	v_mov_b32_e32 v5, v2
	v_lshl_add_u64 v[2:3], v[4:5], 0, v[66:67]
	global_store_dwordx4 v[2:3], v[38:41], off sc1
	v_pk_fma_f32 v[2:3], v[106:107], v[14:15], v[110:111]
	v_pk_fma_f32 v[4:5], v[108:109], v[16:17], v[112:113]
	v_pk_fma_f32 v[2:3], v[18:19], v[102:103], v[2:3]
	v_pk_fma_f32 v[4:5], v[20:21], v[104:105], v[4:5]
	v_pk_fma_f32 v[2:3], v[46:47], v[90:91], v[2:3]
	v_pk_fma_f32 v[4:5], v[48:49], v[92:93], v[4:5]
	v_pk_fma_f32 v[6:7], v[94:95], v[10:11], v[98:99]
	v_pk_fma_f32 v[8:9], v[96:97], v[12:13], v[100:101]
	v_exp_f32_e32 v10, v2
	v_exp_f32_e32 v11, v3
	v_exp_f32_e32 v12, v4
	v_exp_f32_e32 v13, v5
	v_pk_fma_f32 v[6:7], v[22:23], v[78:79], v[6:7]
	v_pk_add_f32 v[10:11], v[10:11], 1.0 op_sel_hi:[1,0]
	v_pk_fma_f32 v[8:9], v[24:25], v[80:81], v[8:9]
	v_pk_add_f32 v[12:13], v[12:13], 1.0 op_sel_hi:[1,0]
	v_rcp_f32_e32 v10, v10
	v_rcp_f32_e32 v11, v11
	v_rcp_f32_e32 v12, v12
	v_rcp_f32_e32 v13, v13
	v_pk_fma_f32 v[6:7], v[50:51], v[74:75], v[6:7]
	v_pk_fma_f32 v[8:9], v[52:53], v[76:77], v[8:9]
	s_movk_i32 s6, 0x7c
	v_pk_mul_f32 v[2:3], v[2:3], v[6:7]
	v_pk_mul_f32 v[4:5], v[4:5], v[8:9]
	v_cmp_ne_u32_e32 vcc, s6, v124
	v_pk_mul_f32 v[2:3], v[10:11], v[2:3]
	v_pk_mul_f32 v[4:5], v[12:13], v[4:5]
	v_cvt_pk_bf16_f32 v30, v2, v3
	s_nop 0
	v_cvt_pk_bf16_f32 v31, v4, v5
	s_and_saveexec_b64 s[6:7], vcc
	s_cbranch_execz .LBB0_1017
	v_add_u32_e32 v186, 0x83, v124
	v_lshl_add_u64 v[2:3], v[120:121], 0, v[186:187]
	v_mov_b64_e32 v[4:5], s[12:13]
	v_mad_u64_u32 v[4:5], s[8:9], v2, s40, v[4:5]
	v_mov_b32_e32 v2, v5
	v_mad_u64_u32 v[2:3], s[8:9], v3, s40, v[2:3]
	v_mov_b32_e32 v5, v2
	v_lshl_add_u64 v[2:3], v[118:119], 1, v[4:5]
	global_store_dwordx4 v[2:3], v[28:31], off sc1
